# K-loops: 59 of 80 LDS-DMA loads on scalar-base addressing (K-step bases recomputed on the SALU)
# speedup vs baseline: 1.0143x; 1.0032x over previous
.LBB0_108:
	s_add_u32 s26, s50, 0xfff80080
	s_addc_u32 s27, s51, -1
	s_add_i32 s67, 0, 0x10000
	v_add_u32_e32 v134, s67, v180
	ds_read_b128 v[182:185], v134
	ds_read_b128 v[186:189], v134 offset:1024
	ds_read_b128 v[190:193], v134 offset:2048
	ds_read_b128 v[194:197], v134 offset:3072
	s_cmp_eq_u32 s66, 28
	s_cselect_b32 s53, s43, s27
	s_cselect_b32 s52, s62, s26
	s_cselect_b32 s27, s23, s65
	s_cselect_b32 s26, s63, s64
	s_add_i32 m0, s7, 0xc000
	ds_read_b128 v[198:201], v181
	ds_read_b128 v[202:205], v181 offset:1024
	ds_read_b128 v[206:209], v181 offset:2048
	ds_read_b128 v[210:213], v181 offset:3072
	ds_read_b128 v[214:217], v181 offset:4096
	ds_read_b128 v[218:221], v181 offset:5120
	ds_read_b128 v[222:225], v181 offset:6144
	ds_read_b128 v[226:229], v181 offset:7168
	global_load_lds_dwordx4 v162, s[50:51]
	s_add_i32 m0, s7, 0xe000
	s_nop 0
	global_load_lds_dwordx4 v164, s[50:51]
	s_waitcnt lgkmcnt(8)
	s_barrier
	s_waitcnt lgkmcnt(0)
	s_setprio 1
	s_waitcnt lgkmcnt(0)
	v_mfma_f32_16x16x32_bf16 v[126:129], v[182:185], v[198:201], v[126:129]
	v_mfma_f32_16x16x32_bf16 v[118:121], v[190:193], v[198:201], v[118:121]
	v_mfma_f32_16x16x32_bf16 v[110:113], v[182:185], v[206:209], v[110:113]
	v_mfma_f32_16x16x32_bf16 v[102:105], v[190:193], v[206:209], v[102:105]
	v_mfma_f32_16x16x32_bf16 v[94:97], v[182:185], v[214:217], v[94:97]
	v_mfma_f32_16x16x32_bf16 v[86:89], v[190:193], v[214:217], v[86:89]
	v_mfma_f32_16x16x32_bf16 v[78:81], v[182:185], v[222:225], v[78:81]
	v_mfma_f32_16x16x32_bf16 v[70:73], v[190:193], v[222:225], v[70:73]
	v_mfma_f32_16x16x32_bf16 v[126:129], v[186:189], v[202:205], v[126:129]
	v_mfma_f32_16x16x32_bf16 v[118:121], v[194:197], v[202:205], v[118:121]
	v_mfma_f32_16x16x32_bf16 v[110:113], v[186:189], v[210:213], v[110:113]
	v_mfma_f32_16x16x32_bf16 v[102:105], v[194:197], v[210:213], v[102:105]
	v_mfma_f32_16x16x32_bf16 v[94:97], v[186:189], v[218:221], v[94:97]
	v_mfma_f32_16x16x32_bf16 v[86:89], v[194:197], v[218:221], v[86:89]
	v_mfma_f32_16x16x32_bf16 v[78:81], v[186:189], v[226:229], v[78:81]
	v_mfma_f32_16x16x32_bf16 v[70:73], v[194:197], v[226:229], v[70:73]
	s_setprio 0
	s_barrier
	s_add_i32 s70, 0, 0x14000
	s_add_i32 s67, s67, s6
	v_add_u32_e32 v134, s70, v180
	s_mov_b32 m0, s67
	ds_read_b128 v[230:233], v134
	ds_read_b128 v[234:237], v134 offset:1024
	ds_read_b128 v[238:241], v134 offset:2048
	ds_read_b128 v[242:245], v134 offset:3072
	global_load_lds_dwordx4 v0, s[26:27]
	v_lshl_add_u64 v[246:247], s[26:27], 0, v[138:139]
	s_add_i32 m0, s67, 0x2000
	s_nop 0
	global_load_lds_dwordx4 v[246:247], off
	s_barrier
	s_waitcnt lgkmcnt(0)
	s_setprio 1
	s_waitcnt lgkmcnt(0)
	v_mfma_f32_16x16x32_bf16 v[122:125], v[230:233], v[198:201], v[122:125]
	v_mfma_f32_16x16x32_bf16 v[114:117], v[238:241], v[198:201], v[114:117]
	v_mfma_f32_16x16x32_bf16 v[106:109], v[230:233], v[206:209], v[106:109]
	v_mfma_f32_16x16x32_bf16 v[98:101], v[238:241], v[206:209], v[98:101]
	v_mfma_f32_16x16x32_bf16 v[90:93], v[230:233], v[214:217], v[90:93]
	v_mfma_f32_16x16x32_bf16 v[82:85], v[238:241], v[214:217], v[82:85]
	v_mfma_f32_16x16x32_bf16 v[74:77], v[230:233], v[222:225], v[74:77]
	v_mfma_f32_16x16x32_bf16 v[66:69], v[238:241], v[222:225], v[66:69]
	v_mfma_f32_16x16x32_bf16 v[122:125], v[234:237], v[202:205], v[122:125]
	v_mfma_f32_16x16x32_bf16 v[114:117], v[242:245], v[202:205], v[114:117]
	v_mfma_f32_16x16x32_bf16 v[106:109], v[234:237], v[210:213], v[106:109]
	v_mfma_f32_16x16x32_bf16 v[98:101], v[242:245], v[210:213], v[98:101]
	v_mfma_f32_16x16x32_bf16 v[90:93], v[234:237], v[218:221], v[90:93]
	v_mfma_f32_16x16x32_bf16 v[82:85], v[242:245], v[218:221], v[82:85]
	v_mfma_f32_16x16x32_bf16 v[74:77], v[234:237], v[226:229], v[74:77]
	v_mfma_f32_16x16x32_bf16 v[66:69], v[242:245], v[226:229], v[66:69]
	s_setprio 0
	s_mov_b32 m0, s7
	v_lshl_add_u64 v[248:249], s[52:53], 0, v[142:143]
	s_barrier
	ds_read_b128 v[198:201], v181 offset:16384
	ds_read_b128 v[202:205], v181 offset:17408
	ds_read_b128 v[206:209], v181 offset:18432
	ds_read_b128 v[210:213], v181 offset:19456
	ds_read_b128 v[214:217], v181 offset:20480
	ds_read_b128 v[218:221], v181 offset:21504
	ds_read_b128 v[222:225], v181 offset:22528
	ds_read_b128 v[226:229], v181 offset:23552
	global_load_lds_dwordx4 v[248:249], off
	v_lshl_add_u64 v[134:135], s[52:53], 0, v[140:141]
	s_mov_b32 m0, s14
	s_nop 0
	global_load_lds_dwordx4 v[134:135], off
	s_barrier
	s_waitcnt lgkmcnt(0)
	s_setprio 1
	s_waitcnt lgkmcnt(0)
	v_mfma_f32_16x16x32_bf16 v[62:65], v[182:185], v[198:201], v[62:65]
	v_mfma_f32_16x16x32_bf16 v[54:57], v[190:193], v[198:201], v[54:57]
	v_mfma_f32_16x16x32_bf16 v[46:49], v[182:185], v[206:209], v[46:49]
	v_mfma_f32_16x16x32_bf16 v[38:41], v[190:193], v[206:209], v[38:41]
	v_mfma_f32_16x16x32_bf16 v[30:33], v[182:185], v[214:217], v[30:33]
	v_mfma_f32_16x16x32_bf16 v[22:25], v[190:193], v[214:217], v[22:25]
	v_mfma_f32_16x16x32_bf16 v[14:17], v[182:185], v[222:225], v[14:17]
	v_mfma_f32_16x16x32_bf16 v[6:9], v[190:193], v[222:225], v[6:9]
	v_mfma_f32_16x16x32_bf16 v[62:65], v[186:189], v[202:205], v[62:65]
	v_mfma_f32_16x16x32_bf16 v[54:57], v[194:197], v[202:205], v[54:57]
	v_mfma_f32_16x16x32_bf16 v[46:49], v[186:189], v[210:213], v[46:49]
	v_mfma_f32_16x16x32_bf16 v[38:41], v[194:197], v[210:213], v[38:41]
	v_mfma_f32_16x16x32_bf16 v[30:33], v[186:189], v[218:221], v[30:33]
	v_mfma_f32_16x16x32_bf16 v[22:25], v[194:197], v[218:221], v[22:25]
	v_mfma_f32_16x16x32_bf16 v[14:17], v[186:189], v[226:229], v[14:17]
	v_mfma_f32_16x16x32_bf16 v[6:9], v[194:197], v[226:229], v[6:9]
	s_setprio 0
	s_barrier
	s_add_u32 s68, s26, 0x80000
	s_addc_u32 s69, s27, 0
	s_add_i32 s67, s70, s6
	s_mov_b32 m0, s67
	s_nop 0
	global_load_lds_dwordx4 v0, s[68:69]
	s_add_i32 m0, s67, 0x2000
	s_nop 0
	global_load_lds_dwordx4 v138, s[68:69]
	s_waitcnt vmcnt(6)
	s_barrier
	s_setprio 1
	v_mfma_f32_16x16x32_bf16 v[58:61], v[230:233], v[198:201], v[58:61]
	v_mfma_f32_16x16x32_bf16 v[50:53], v[238:241], v[198:201], v[50:53]
	v_mfma_f32_16x16x32_bf16 v[42:45], v[230:233], v[206:209], v[42:45]
	v_mfma_f32_16x16x32_bf16 v[34:37], v[238:241], v[206:209], v[34:37]
	v_mfma_f32_16x16x32_bf16 v[26:29], v[230:233], v[214:217], v[26:29]
	v_mfma_f32_16x16x32_bf16 v[18:21], v[238:241], v[214:217], v[18:21]
	v_mfma_f32_16x16x32_bf16 v[10:13], v[230:233], v[222:225], v[10:13]
	v_mfma_f32_16x16x32_bf16 v[2:5], v[238:241], v[222:225], v[2:5]
	v_mfma_f32_16x16x32_bf16 v[58:61], v[234:237], v[202:205], v[58:61]
	v_mfma_f32_16x16x32_bf16 v[50:53], v[242:245], v[202:205], v[50:53]
	v_mfma_f32_16x16x32_bf16 v[42:45], v[234:237], v[210:213], v[42:45]
	v_mfma_f32_16x16x32_bf16 v[34:37], v[242:245], v[210:213], v[34:37]
	v_mfma_f32_16x16x32_bf16 v[26:29], v[234:237], v[218:221], v[26:29]
	v_mfma_f32_16x16x32_bf16 v[18:21], v[242:245], v[218:221], v[18:21]
	v_mfma_f32_16x16x32_bf16 v[10:13], v[234:237], v[226:229], v[10:13]
	v_mfma_f32_16x16x32_bf16 v[2:5], v[242:245], v[226:229], v[2:5]
	s_setprio 0
	s_add_i32 s67, 0, 0x18000
	v_add_u32_e32 v194, s67, v180
	s_barrier
	ds_read_b128 v[182:185], v194
	ds_read_b128 v[186:189], v194 offset:1024
	ds_read_b128 v[190:193], v194 offset:2048
	ds_read_b128 v[194:197], v194 offset:3072
	s_add_u32 s52, s52, 0x80000
	s_addc_u32 s53, s53, 0
	s_mov_b32 m0, s54
	ds_read_b128 v[198:201], v181 offset:32768
	ds_read_b128 v[202:205], v181 offset:33792
	ds_read_b128 v[206:209], v181 offset:34816
	ds_read_b128 v[210:213], v181 offset:35840
	ds_read_b128 v[214:217], v181 offset:36864
	ds_read_b128 v[218:221], v181 offset:37888
	ds_read_b128 v[222:225], v181 offset:38912
	ds_read_b128 v[226:229], v181 offset:39936
	global_load_lds_dwordx4 v142, s[52:53]
	s_mov_b32 m0, s55
	s_nop 0
	global_load_lds_dwordx4 v140, s[52:53]
	s_waitcnt lgkmcnt(8)
	s_barrier
	s_waitcnt lgkmcnt(0)
	s_setprio 1
	s_waitcnt lgkmcnt(0)
	v_mfma_f32_16x16x32_bf16 v[126:129], v[182:185], v[198:201], v[126:129]
	v_mfma_f32_16x16x32_bf16 v[118:121], v[190:193], v[198:201], v[118:121]
	v_mfma_f32_16x16x32_bf16 v[110:113], v[182:185], v[206:209], v[110:113]
	v_mfma_f32_16x16x32_bf16 v[102:105], v[190:193], v[206:209], v[102:105]
	v_mfma_f32_16x16x32_bf16 v[94:97], v[182:185], v[214:217], v[94:97]
	v_mfma_f32_16x16x32_bf16 v[86:89], v[190:193], v[214:217], v[86:89]
	v_mfma_f32_16x16x32_bf16 v[78:81], v[182:185], v[222:225], v[78:81]
	v_mfma_f32_16x16x32_bf16 v[70:73], v[190:193], v[222:225], v[70:73]
	v_mfma_f32_16x16x32_bf16 v[126:129], v[186:189], v[202:205], v[126:129]
	v_mfma_f32_16x16x32_bf16 v[118:121], v[194:197], v[202:205], v[118:121]
	v_mfma_f32_16x16x32_bf16 v[110:113], v[186:189], v[210:213], v[110:113]
	v_mfma_f32_16x16x32_bf16 v[102:105], v[194:197], v[210:213], v[102:105]
	v_mfma_f32_16x16x32_bf16 v[94:97], v[186:189], v[218:221], v[94:97]
	v_mfma_f32_16x16x32_bf16 v[86:89], v[194:197], v[218:221], v[86:89]
	v_mfma_f32_16x16x32_bf16 v[78:81], v[186:189], v[226:229], v[78:81]
	v_mfma_f32_16x16x32_bf16 v[70:73], v[194:197], v[226:229], v[70:73]
	s_setprio 0
	s_barrier
	s_add_i32 s52, 0, 0x1c000
	s_add_i32 s53, s67, s6
	v_add_u32_e32 v242, s52, v180
	s_add_u32 s100, s26, s10
	s_addc_u32 s101, s27, s11
	s_mov_b32 m0, s53
	ds_read_b128 v[230:233], v242
	ds_read_b128 v[234:237], v242 offset:1024
	ds_read_b128 v[238:241], v242 offset:2048
	ds_read_b128 v[242:245], v242 offset:3072
	global_load_lds_dwordx4 v0, s[100:101]
	s_add_u32 s100, s26, s10
	s_addc_u32 s101, s27, s11
	s_add_i32 m0, s53, 0x2000
	s_nop 0
	global_load_lds_dwordx4 v138, s[100:101]
	s_barrier
	s_waitcnt lgkmcnt(0)
	s_setprio 1
	s_waitcnt lgkmcnt(0)
	v_mfma_f32_16x16x32_bf16 v[122:125], v[230:233], v[198:201], v[122:125]
	v_mfma_f32_16x16x32_bf16 v[114:117], v[238:241], v[198:201], v[114:117]
	v_mfma_f32_16x16x32_bf16 v[106:109], v[230:233], v[206:209], v[106:109]
	v_mfma_f32_16x16x32_bf16 v[98:101], v[238:241], v[206:209], v[98:101]
	v_mfma_f32_16x16x32_bf16 v[90:93], v[230:233], v[214:217], v[90:93]
	v_mfma_f32_16x16x32_bf16 v[82:85], v[238:241], v[214:217], v[82:85]
	v_mfma_f32_16x16x32_bf16 v[74:77], v[230:233], v[222:225], v[74:77]
	v_mfma_f32_16x16x32_bf16 v[66:69], v[238:241], v[222:225], v[66:69]
	v_mfma_f32_16x16x32_bf16 v[122:125], v[234:237], v[202:205], v[122:125]
	v_mfma_f32_16x16x32_bf16 v[114:117], v[242:245], v[202:205], v[114:117]
	v_mfma_f32_16x16x32_bf16 v[106:109], v[234:237], v[210:213], v[106:109]
	v_mfma_f32_16x16x32_bf16 v[98:101], v[242:245], v[210:213], v[98:101]
	v_mfma_f32_16x16x32_bf16 v[90:93], v[234:237], v[218:221], v[90:93]
	v_mfma_f32_16x16x32_bf16 v[82:85], v[242:245], v[218:221], v[82:85]
	v_mfma_f32_16x16x32_bf16 v[74:77], v[234:237], v[226:229], v[74:77]
	v_mfma_f32_16x16x32_bf16 v[66:69], v[242:245], v[226:229], v[66:69]
	s_setprio 0
	s_mov_b32 m0, s57
	v_lshl_add_u64 v[166:167], v[248:249], 0, s[10:11]
	s_barrier
	ds_read_b128 v[198:201], v181 offset:49152
	ds_read_b128 v[202:205], v181 offset:50176
	ds_read_b128 v[206:209], v181 offset:51200
	ds_read_b128 v[210:213], v181 offset:52224
	ds_read_b128 v[214:217], v181 offset:53248
	ds_read_b128 v[218:221], v181 offset:54272
	ds_read_b128 v[222:225], v181 offset:55296
	ds_read_b128 v[226:229], v181 offset:56320
	global_load_lds_dwordx4 v[166:167], off
	v_lshl_add_u64 v[134:135], v[134:135], 0, s[10:11]
	s_mov_b32 m0, s58
	s_nop 0
	global_load_lds_dwordx4 v[134:135], off
	s_barrier
	s_waitcnt lgkmcnt(0)
	s_setprio 1
	s_waitcnt lgkmcnt(0)
	v_mfma_f32_16x16x32_bf16 v[62:65], v[182:185], v[198:201], v[62:65]
	v_mfma_f32_16x16x32_bf16 v[54:57], v[190:193], v[198:201], v[54:57]
	v_mfma_f32_16x16x32_bf16 v[46:49], v[182:185], v[206:209], v[46:49]
	v_mfma_f32_16x16x32_bf16 v[38:41], v[190:193], v[206:209], v[38:41]
	v_mfma_f32_16x16x32_bf16 v[30:33], v[182:185], v[214:217], v[30:33]
	v_mfma_f32_16x16x32_bf16 v[22:25], v[190:193], v[214:217], v[22:25]
	v_mfma_f32_16x16x32_bf16 v[14:17], v[182:185], v[222:225], v[14:17]
	v_mfma_f32_16x16x32_bf16 v[6:9], v[190:193], v[222:225], v[6:9]
	v_mfma_f32_16x16x32_bf16 v[62:65], v[186:189], v[202:205], v[62:65]
	v_mfma_f32_16x16x32_bf16 v[54:57], v[194:197], v[202:205], v[54:57]
	v_mfma_f32_16x16x32_bf16 v[46:49], v[186:189], v[210:213], v[46:49]
	v_mfma_f32_16x16x32_bf16 v[38:41], v[194:197], v[210:213], v[38:41]
	v_mfma_f32_16x16x32_bf16 v[30:33], v[186:189], v[218:221], v[30:33]
	v_mfma_f32_16x16x32_bf16 v[22:25], v[194:197], v[218:221], v[22:25]
	v_mfma_f32_16x16x32_bf16 v[14:17], v[186:189], v[226:229], v[14:17]
	v_mfma_f32_16x16x32_bf16 v[6:9], v[194:197], v[226:229], v[6:9]
	s_setprio 0
	s_barrier
	s_add_u32 s26, s26, 0x80080
	s_addc_u32 s27, s27, 0
	s_add_i32 s52, s52, s6
	s_mov_b32 m0, s52
	s_nop 0
	global_load_lds_dwordx4 v0, s[26:27]
	s_add_i32 m0, s52, 0x2000
	s_nop 0
	global_load_lds_dwordx4 v138, s[26:27]
	s_waitcnt vmcnt(6)
	s_barrier
	s_setprio 1
	v_mfma_f32_16x16x32_bf16 v[58:61], v[230:233], v[198:201], v[58:61]
	v_mfma_f32_16x16x32_bf16 v[50:53], v[238:241], v[198:201], v[50:53]
	v_mfma_f32_16x16x32_bf16 v[42:45], v[230:233], v[206:209], v[42:45]
	v_mfma_f32_16x16x32_bf16 v[34:37], v[238:241], v[206:209], v[34:37]
	v_mfma_f32_16x16x32_bf16 v[26:29], v[230:233], v[214:217], v[26:29]
	v_mfma_f32_16x16x32_bf16 v[18:21], v[238:241], v[214:217], v[18:21]
	v_mfma_f32_16x16x32_bf16 v[10:13], v[230:233], v[222:225], v[10:13]
	v_mfma_f32_16x16x32_bf16 v[2:5], v[238:241], v[222:225], v[2:5]
	v_mfma_f32_16x16x32_bf16 v[58:61], v[234:237], v[202:205], v[58:61]
	v_mfma_f32_16x16x32_bf16 v[50:53], v[242:245], v[202:205], v[50:53]
	v_mfma_f32_16x16x32_bf16 v[42:45], v[234:237], v[210:213], v[42:45]
	v_mfma_f32_16x16x32_bf16 v[34:37], v[242:245], v[210:213], v[34:37]
	v_mfma_f32_16x16x32_bf16 v[26:29], v[234:237], v[218:221], v[26:29]
	v_mfma_f32_16x16x32_bf16 v[18:21], v[242:245], v[218:221], v[18:21]
	v_mfma_f32_16x16x32_bf16 v[10:13], v[234:237], v[226:229], v[10:13]
	v_mfma_f32_16x16x32_bf16 v[2:5], v[242:245], v[226:229], v[2:5]
	s_setprio 0
	s_add_i32 s66, s66, 2
	s_add_u32 s50, s50, 0x100
	s_addc_u32 s51, s51, 0
	s_add_u32 s64, s64, 0x100
	s_addc_u32 s65, s65, 0
	s_cmp_gt_u32 s66, 29
	s_barrier
	s_cbranch_scc0 .LBB0_108
	v_mul_f32_e32 v134, 0xbfb8aa3b, v126
	v_exp_f32_e32 v134, v134
	s_lshl_b32 s23, s61, 7
	s_or_b32 s23, s23, s56
	s_ashr_i32 s23, s23, 6
	v_add_f32_e32 v134, 1.0, v134
	v_rcp_f32_e32 v134, v134
	s_mul_i32 s26, s60, 0x58
	s_ashr_i32 s43, s23, 31
	s_mul_hi_i32 s27, s60, 0x58
	v_mul_f32_e32 v126, v126, v134
	v_mul_f32_e32 v122, v126, v122
	v_mul_f32_e32 v126, 0xbfb8aa3b, v118
	v_exp_f32_e32 v126, v126
	s_add_u32 s26, s26, s23
	s_addc_u32 s27, s27, s43
	s_lshl_b64 s[26:27], s[26:27], 15
	v_add_f32_e32 v126, 1.0, v126
	v_rcp_f32_e32 v126, v126
	v_lshl_add_u64 v[166:167], v[144:145], 0, s[26:27]
	s_and_b64 vcc, exec, s[38:39]
	s_mov_b32 s61, s22
	v_mul_f32_e32 v118, v118, v126
	v_mul_f32_e32 v126, v118, v114
	v_mul_f32_e32 v114, 0xbfb8aa3b, v127
	v_mul_f32_e32 v118, 0xbfb8aa3b, v119
	v_exp_f32_e32 v114, v114
	v_exp_f32_e32 v118, v118
	s_mov_b32 s60, s42
	s_mov_b64 s[26:27], s[24:25]
	v_add_f32_e32 v114, 1.0, v114
	v_add_f32_e32 v118, 1.0, v118
	v_rcp_f32_e32 v114, v114
	v_rcp_f32_e32 v118, v118
	s_mov_b64 s[50:51], s[48:49]
	v_readlane_b32 s70, v254, 38
	v_mul_f32_e32 v114, v127, v114
	v_mul_f32_e32 v118, v119, v118
	v_mul_f32_e32 v114, v114, v123
	v_mul_f32_e32 v123, v118, v115
	v_mul_f32_e32 v118, 0xbfb8aa3b, v120
	v_exp_f32_e32 v118, v118
	v_mul_f32_e32 v115, 0xbfb8aa3b, v128
	v_exp_f32_e32 v115, v115
	v_cvt_pk_bf16_f32 v114, v122, v114
	v_add_f32_e32 v118, 1.0, v118
	v_rcp_f32_e32 v118, v118
	v_add_f32_e32 v115, 1.0, v115
	v_rcp_f32_e32 v115, v115
	v_mul_f32_e32 v118, v120, v118
	v_mul_f32_e32 v120, v118, v116
	v_mul_f32_e32 v116, 0xbfb8aa3b, v129
	v_mul_f32_e32 v118, 0xbfb8aa3b, v121
	v_exp_f32_e32 v116, v116
	v_exp_f32_e32 v118, v118
	v_mul_f32_e32 v115, v128, v115
	v_mul_f32_e32 v115, v115, v124
	v_add_f32_e32 v116, 1.0, v116
	v_add_f32_e32 v118, 1.0, v118
	v_rcp_f32_e32 v116, v116
	v_rcp_f32_e32 v118, v118
	v_mul_f32_e32 v116, v129, v116
	v_mul_f32_e32 v118, v121, v118
	v_mul_f32_e32 v116, v116, v125
	v_mul_f32_e32 v117, v118, v117
	v_lshl_add_u64 v[118:119], v[166:167], 0, v[146:147]
	v_cvt_pk_bf16_f32 v115, v115, v116
	v_cvt_pk_bf16_f32 v116, v126, v123
	v_cvt_pk_bf16_f32 v117, v120, v117
	global_store_dwordx4 v[118:119], v[114:117], off
	s_nop 1
	v_mul_f32_e32 v114, 0xbfb8aa3b, v110
	v_exp_f32_e32 v114, v114
	s_nop 0
	v_add_f32_e32 v114, 1.0, v114
	v_rcp_f32_e32 v114, v114
	s_nop 0
	v_mul_f32_e32 v110, v110, v114
	v_mul_f32_e32 v106, v110, v106
	v_mul_f32_e32 v110, 0xbfb8aa3b, v102
	v_exp_f32_e32 v110, v110
	s_nop 0
	v_add_f32_e32 v110, 1.0, v110
	v_rcp_f32_e32 v110, v110
	s_nop 0
	v_mul_f32_e32 v102, v102, v110
	v_mul_f32_e32 v110, v102, v98
	v_mul_f32_e32 v98, 0xbfb8aa3b, v111
	v_mul_f32_e32 v102, 0xbfb8aa3b, v103
	v_exp_f32_e32 v98, v98
	v_exp_f32_e32 v102, v102
	v_add_f32_e32 v98, 1.0, v98
	v_add_f32_e32 v102, 1.0, v102
	v_rcp_f32_e32 v98, v98
	v_rcp_f32_e32 v102, v102
	v_mul_f32_e32 v98, v111, v98
	v_mul_f32_e32 v102, v103, v102
	v_mul_f32_e32 v98, v98, v107
	v_mul_f32_e32 v107, v102, v99
	v_mul_f32_e32 v102, 0xbfb8aa3b, v104
	v_exp_f32_e32 v102, v102
	v_mul_f32_e32 v99, 0xbfb8aa3b, v112
	v_exp_f32_e32 v99, v99
	v_cvt_pk_bf16_f32 v98, v106, v98
	v_add_f32_e32 v102, 1.0, v102
	v_rcp_f32_e32 v102, v102
	v_add_f32_e32 v99, 1.0, v99
	v_rcp_f32_e32 v99, v99
	v_mul_f32_e32 v102, v104, v102
	v_mul_f32_e32 v104, v102, v100
	v_mul_f32_e32 v100, 0xbfb8aa3b, v113
	v_mul_f32_e32 v102, 0xbfb8aa3b, v105
	v_exp_f32_e32 v100, v100
	v_exp_f32_e32 v102, v102
	v_mul_f32_e32 v99, v112, v99
	v_mul_f32_e32 v99, v99, v108
	v_add_f32_e32 v100, 1.0, v100
	v_add_f32_e32 v102, 1.0, v102
	v_rcp_f32_e32 v100, v100
	v_rcp_f32_e32 v102, v102
	v_mul_f32_e32 v100, v113, v100
	v_mul_f32_e32 v102, v105, v102
	v_mul_f32_e32 v100, v100, v109
	v_mul_f32_e32 v101, v102, v101
	v_lshl_add_u64 v[102:103], v[166:167], 0, v[148:149]
	v_cvt_pk_bf16_f32 v99, v99, v100
	v_cvt_pk_bf16_f32 v100, v110, v107
	v_cvt_pk_bf16_f32 v101, v104, v101
	global_store_dwordx4 v[102:103], v[98:101], off
	s_nop 1
	v_mul_f32_e32 v98, 0xbfb8aa3b, v94
	v_exp_f32_e32 v98, v98
	s_nop 0
	v_add_f32_e32 v98, 1.0, v98
	v_rcp_f32_e32 v98, v98
	s_nop 0
	v_mul_f32_e32 v94, v94, v98
	v_mul_f32_e32 v90, v94, v90
	v_mul_f32_e32 v94, 0xbfb8aa3b, v86
	v_exp_f32_e32 v94, v94
	s_nop 0
	v_add_f32_e32 v94, 1.0, v94
	v_rcp_f32_e32 v94, v94
	s_nop 0
	v_mul_f32_e32 v86, v86, v94
	v_mul_f32_e32 v94, v86, v82
	v_mul_f32_e32 v82, 0xbfb8aa3b, v95
	v_mul_f32_e32 v86, 0xbfb8aa3b, v87
	v_exp_f32_e32 v82, v82
	v_exp_f32_e32 v86, v86
	v_add_f32_e32 v82, 1.0, v82
	v_add_f32_e32 v86, 1.0, v86
	v_rcp_f32_e32 v82, v82
	v_rcp_f32_e32 v86, v86
	v_mul_f32_e32 v82, v95, v82
	v_mul_f32_e32 v86, v87, v86
	v_mul_f32_e32 v82, v82, v91
	v_mul_f32_e32 v91, v86, v83
	v_mul_f32_e32 v86, 0xbfb8aa3b, v88
	v_exp_f32_e32 v86, v86
	v_mul_f32_e32 v83, 0xbfb8aa3b, v96
	v_exp_f32_e32 v83, v83
	v_cvt_pk_bf16_f32 v82, v90, v82
	v_add_f32_e32 v86, 1.0, v86
	v_rcp_f32_e32 v86, v86
	v_add_f32_e32 v83, 1.0, v83
	v_rcp_f32_e32 v83, v83
	v_mul_f32_e32 v86, v88, v86
	v_mul_f32_e32 v88, v86, v84
	v_mul_f32_e32 v84, 0xbfb8aa3b, v97
	v_mul_f32_e32 v86, 0xbfb8aa3b, v89
	v_exp_f32_e32 v84, v84
	v_exp_f32_e32 v86, v86
	v_mul_f32_e32 v83, v96, v83
	v_mul_f32_e32 v83, v83, v92
	v_add_f32_e32 v84, 1.0, v84
	v_add_f32_e32 v86, 1.0, v86
	v_rcp_f32_e32 v84, v84
	v_rcp_f32_e32 v86, v86
	v_mul_f32_e32 v84, v97, v84
	v_mul_f32_e32 v86, v89, v86
	v_mul_f32_e32 v84, v84, v93
	v_mul_f32_e32 v85, v86, v85
	v_lshl_add_u64 v[86:87], v[166:167], 0, v[150:151]
	v_cvt_pk_bf16_f32 v83, v83, v84
	v_cvt_pk_bf16_f32 v84, v94, v91
	v_cvt_pk_bf16_f32 v85, v88, v85
	global_store_dwordx4 v[86:87], v[82:85], off
	s_nop 1
	v_mul_f32_e32 v82, 0xbfb8aa3b, v78
	v_exp_f32_e32 v82, v82
	s_nop 0
	v_add_f32_e32 v82, 1.0, v82
	v_rcp_f32_e32 v82, v82
	s_nop 0
	v_mul_f32_e32 v78, v78, v82
	v_mul_f32_e32 v74, v78, v74
	v_mul_f32_e32 v78, 0xbfb8aa3b, v70
	v_exp_f32_e32 v78, v78
	s_nop 0
	v_add_f32_e32 v78, 1.0, v78
	v_rcp_f32_e32 v78, v78
	s_nop 0
	v_mul_f32_e32 v70, v70, v78
	v_mul_f32_e32 v78, v70, v66
	v_mul_f32_e32 v66, 0xbfb8aa3b, v79
	v_mul_f32_e32 v70, 0xbfb8aa3b, v71
	v_exp_f32_e32 v66, v66
	v_exp_f32_e32 v70, v70
	v_add_f32_e32 v66, 1.0, v66
	v_add_f32_e32 v70, 1.0, v70
	v_rcp_f32_e32 v66, v66
	v_rcp_f32_e32 v70, v70
	v_mul_f32_e32 v66, v79, v66
	v_mul_f32_e32 v70, v71, v70
	v_mul_f32_e32 v66, v66, v75
	v_mul_f32_e32 v75, v70, v67
	v_mul_f32_e32 v70, 0xbfb8aa3b, v72
	v_exp_f32_e32 v70, v70
	v_mul_f32_e32 v67, 0xbfb8aa3b, v80
	v_exp_f32_e32 v67, v67
	v_cvt_pk_bf16_f32 v66, v74, v66
	v_add_f32_e32 v70, 1.0, v70
	v_rcp_f32_e32 v70, v70
	v_add_f32_e32 v67, 1.0, v67
	v_rcp_f32_e32 v67, v67
	v_mul_f32_e32 v70, v72, v70
	v_mul_f32_e32 v72, v70, v68
	v_mul_f32_e32 v68, 0xbfb8aa3b, v81
	v_mul_f32_e32 v70, 0xbfb8aa3b, v73
	v_exp_f32_e32 v68, v68
	v_exp_f32_e32 v70, v70
	v_mul_f32_e32 v67, v80, v67
	v_mul_f32_e32 v67, v67, v76
	v_add_f32_e32 v68, 1.0, v68
	v_add_f32_e32 v70, 1.0, v70
	v_rcp_f32_e32 v68, v68
	v_rcp_f32_e32 v70, v70
	v_mul_f32_e32 v68, v81, v68
	v_mul_f32_e32 v70, v73, v70
	v_mul_f32_e32 v68, v68, v77
	v_mul_f32_e32 v69, v70, v69
	v_lshl_add_u64 v[70:71], v[166:167], 0, v[152:153]
	v_cvt_pk_bf16_f32 v67, v67, v68
	v_cvt_pk_bf16_f32 v68, v78, v75
	v_cvt_pk_bf16_f32 v69, v72, v69
	global_store_dwordx4 v[70:71], v[66:69], off
	s_nop 1
	v_mul_f32_e32 v66, 0xbfb8aa3b, v62
	v_exp_f32_e32 v66, v66
	s_nop 0
	v_add_f32_e32 v66, 1.0, v66
	v_rcp_f32_e32 v66, v66
	s_nop 0
	v_mul_f32_e32 v62, v62, v66
	v_mul_f32_e32 v58, v62, v58
	v_mul_f32_e32 v62, 0xbfb8aa3b, v54
	v_exp_f32_e32 v62, v62
	s_nop 0
	v_add_f32_e32 v62, 1.0, v62
	v_rcp_f32_e32 v62, v62
	s_nop 0
	v_mul_f32_e32 v54, v54, v62
	v_mul_f32_e32 v62, v54, v50
	v_mul_f32_e32 v50, 0xbfb8aa3b, v63
	v_mul_f32_e32 v54, 0xbfb8aa3b, v55
	v_exp_f32_e32 v50, v50
	v_exp_f32_e32 v54, v54
	v_add_f32_e32 v50, 1.0, v50
	v_add_f32_e32 v54, 1.0, v54
	v_rcp_f32_e32 v50, v50
	v_rcp_f32_e32 v54, v54
	v_mul_f32_e32 v50, v63, v50
	v_mul_f32_e32 v54, v55, v54
	v_mul_f32_e32 v50, v50, v59
	v_mul_f32_e32 v59, v54, v51
	v_mul_f32_e32 v54, 0xbfb8aa3b, v56
	v_exp_f32_e32 v54, v54
	v_mul_f32_e32 v51, 0xbfb8aa3b, v64
	v_exp_f32_e32 v51, v51
	v_cvt_pk_bf16_f32 v50, v58, v50
	v_add_f32_e32 v54, 1.0, v54
	v_rcp_f32_e32 v54, v54
	v_add_f32_e32 v51, 1.0, v51
	v_rcp_f32_e32 v51, v51
	v_mul_f32_e32 v54, v56, v54
	v_mul_f32_e32 v56, v54, v52
	v_mul_f32_e32 v52, 0xbfb8aa3b, v65
	v_mul_f32_e32 v54, 0xbfb8aa3b, v57
	v_exp_f32_e32 v52, v52
	v_exp_f32_e32 v54, v54
	v_mul_f32_e32 v51, v64, v51
	v_mul_f32_e32 v51, v51, v60
	v_add_f32_e32 v52, 1.0, v52
	v_add_f32_e32 v54, 1.0, v54
	v_rcp_f32_e32 v52, v52
	v_rcp_f32_e32 v54, v54
	v_mul_f32_e32 v52, v65, v52
	v_mul_f32_e32 v54, v57, v54
	v_mul_f32_e32 v52, v52, v61
	v_mul_f32_e32 v53, v54, v53
	v_lshl_add_u64 v[54:55], v[166:167], 0, v[154:155]
	v_cvt_pk_bf16_f32 v51, v51, v52
	v_cvt_pk_bf16_f32 v52, v62, v59
	v_cvt_pk_bf16_f32 v53, v56, v53
	global_store_dwordx4 v[54:55], v[50:53], off
	s_nop 1
	v_mul_f32_e32 v50, 0xbfb8aa3b, v46
	v_exp_f32_e32 v50, v50
	s_nop 0
	v_add_f32_e32 v50, 1.0, v50
	v_rcp_f32_e32 v50, v50
	s_nop 0
	v_mul_f32_e32 v46, v46, v50
	v_mul_f32_e32 v42, v46, v42
	v_mul_f32_e32 v46, 0xbfb8aa3b, v38
	v_exp_f32_e32 v46, v46
	s_nop 0
	v_add_f32_e32 v46, 1.0, v46
	v_rcp_f32_e32 v46, v46
	s_nop 0
	v_mul_f32_e32 v38, v38, v46
	v_mul_f32_e32 v46, v38, v34
	v_mul_f32_e32 v34, 0xbfb8aa3b, v47
	v_mul_f32_e32 v38, 0xbfb8aa3b, v39
	v_exp_f32_e32 v34, v34
	v_exp_f32_e32 v38, v38
	v_add_f32_e32 v34, 1.0, v34
	v_add_f32_e32 v38, 1.0, v38
	v_rcp_f32_e32 v34, v34
	v_rcp_f32_e32 v38, v38
	v_mul_f32_e32 v34, v47, v34
	v_mul_f32_e32 v38, v39, v38
	v_mul_f32_e32 v34, v34, v43
	v_mul_f32_e32 v43, v38, v35
	v_mul_f32_e32 v38, 0xbfb8aa3b, v40
	v_exp_f32_e32 v38, v38
	v_mul_f32_e32 v35, 0xbfb8aa3b, v48
	v_exp_f32_e32 v35, v35
	v_cvt_pk_bf16_f32 v34, v42, v34
	v_add_f32_e32 v38, 1.0, v38
	v_rcp_f32_e32 v38, v38
	v_add_f32_e32 v35, 1.0, v35
	v_rcp_f32_e32 v35, v35
	v_mul_f32_e32 v38, v40, v38
	v_mul_f32_e32 v40, v38, v36
	v_mul_f32_e32 v36, 0xbfb8aa3b, v49
	v_mul_f32_e32 v38, 0xbfb8aa3b, v41
	v_exp_f32_e32 v36, v36
	v_exp_f32_e32 v38, v38
	v_mul_f32_e32 v35, v48, v35
	v_mul_f32_e32 v35, v35, v44
	v_add_f32_e32 v36, 1.0, v36
	v_add_f32_e32 v38, 1.0, v38
	v_rcp_f32_e32 v36, v36
	v_rcp_f32_e32 v38, v38
	v_mul_f32_e32 v36, v49, v36
	v_mul_f32_e32 v38, v41, v38
	v_mul_f32_e32 v36, v36, v45
	v_mul_f32_e32 v37, v38, v37
	v_lshl_add_u64 v[38:39], v[166:167], 0, v[156:157]
	v_cvt_pk_bf16_f32 v35, v35, v36
	v_cvt_pk_bf16_f32 v36, v46, v43
	v_cvt_pk_bf16_f32 v37, v40, v37
	global_store_dwordx4 v[38:39], v[34:37], off
	s_nop 1
	v_mul_f32_e32 v34, 0xbfb8aa3b, v30
	v_exp_f32_e32 v34, v34
	s_nop 0
	v_add_f32_e32 v34, 1.0, v34
	v_rcp_f32_e32 v34, v34
	s_nop 0
	v_mul_f32_e32 v30, v30, v34
	v_mul_f32_e32 v26, v30, v26
	v_mul_f32_e32 v30, 0xbfb8aa3b, v22
	v_exp_f32_e32 v30, v30
	s_nop 0
	v_add_f32_e32 v30, 1.0, v30
	v_rcp_f32_e32 v30, v30
	s_nop 0
	v_mul_f32_e32 v22, v22, v30
	v_mul_f32_e32 v30, v22, v18
	v_mul_f32_e32 v18, 0xbfb8aa3b, v31
	v_mul_f32_e32 v22, 0xbfb8aa3b, v23
	v_exp_f32_e32 v18, v18
	v_exp_f32_e32 v22, v22
	v_add_f32_e32 v18, 1.0, v18
	v_add_f32_e32 v22, 1.0, v22
	v_rcp_f32_e32 v18, v18
	v_rcp_f32_e32 v22, v22
	v_mul_f32_e32 v18, v31, v18
	v_mul_f32_e32 v22, v23, v22
	v_mul_f32_e32 v18, v18, v27
	v_mul_f32_e32 v27, v22, v19
	v_mul_f32_e32 v22, 0xbfb8aa3b, v24
	v_exp_f32_e32 v22, v22
	v_mul_f32_e32 v19, 0xbfb8aa3b, v32
	v_exp_f32_e32 v19, v19
	v_cvt_pk_bf16_f32 v18, v26, v18
	v_add_f32_e32 v22, 1.0, v22
	v_rcp_f32_e32 v22, v22
	v_add_f32_e32 v19, 1.0, v19
	v_rcp_f32_e32 v19, v19
	v_mul_f32_e32 v22, v24, v22
	v_mul_f32_e32 v24, v22, v20
	v_mul_f32_e32 v20, 0xbfb8aa3b, v33
	v_mul_f32_e32 v22, 0xbfb8aa3b, v25
	v_exp_f32_e32 v20, v20
	v_exp_f32_e32 v22, v22
	v_mul_f32_e32 v19, v32, v19
	v_mul_f32_e32 v19, v19, v28
	v_add_f32_e32 v20, 1.0, v20
	v_add_f32_e32 v22, 1.0, v22
	v_rcp_f32_e32 v20, v20
	v_rcp_f32_e32 v22, v22
	v_mul_f32_e32 v20, v33, v20
	v_mul_f32_e32 v22, v25, v22
	v_mul_f32_e32 v20, v20, v29
	v_mul_f32_e32 v21, v22, v21
	v_lshl_add_u64 v[22:23], v[166:167], 0, v[158:159]
	v_cvt_pk_bf16_f32 v19, v19, v20
	v_cvt_pk_bf16_f32 v20, v30, v27
	v_cvt_pk_bf16_f32 v21, v24, v21
	global_store_dwordx4 v[22:23], v[18:21], off
	s_nop 1
	v_mul_f32_e32 v18, 0xbfb8aa3b, v14
	v_exp_f32_e32 v18, v18
	s_nop 0
	v_add_f32_e32 v18, 1.0, v18
	v_rcp_f32_e32 v18, v18
	s_nop 0
	v_mul_f32_e32 v14, v14, v18
	v_mul_f32_e32 v10, v14, v10
	v_mul_f32_e32 v14, 0xbfb8aa3b, v6
	v_exp_f32_e32 v14, v14
	s_nop 0
	v_add_f32_e32 v14, 1.0, v14
	v_rcp_f32_e32 v14, v14
	s_nop 0
	v_mul_f32_e32 v6, v6, v14
	v_mul_f32_e32 v14, v6, v2
	v_mul_f32_e32 v2, 0xbfb8aa3b, v15
	v_mul_f32_e32 v6, 0xbfb8aa3b, v7
	v_exp_f32_e32 v2, v2
	v_exp_f32_e32 v6, v6
	v_add_f32_e32 v2, 1.0, v2
	v_add_f32_e32 v6, 1.0, v6
	v_rcp_f32_e32 v2, v2
	v_rcp_f32_e32 v6, v6
	v_mul_f32_e32 v2, v15, v2
	v_mul_f32_e32 v6, v7, v6
	v_mul_f32_e32 v2, v2, v11
	v_mul_f32_e32 v11, v6, v3
	v_mul_f32_e32 v6, 0xbfb8aa3b, v8
	v_exp_f32_e32 v6, v6
	v_mul_f32_e32 v3, 0xbfb8aa3b, v16
	v_exp_f32_e32 v3, v3
	v_cvt_pk_bf16_f32 v2, v10, v2
	v_add_f32_e32 v6, 1.0, v6
	v_rcp_f32_e32 v6, v6
	v_add_f32_e32 v3, 1.0, v3
	v_rcp_f32_e32 v3, v3
	v_mul_f32_e32 v6, v8, v6
	v_mul_f32_e32 v8, v6, v4
	v_mul_f32_e32 v4, 0xbfb8aa3b, v17
	v_mul_f32_e32 v6, 0xbfb8aa3b, v9
	v_exp_f32_e32 v4, v4
	v_exp_f32_e32 v6, v6
	v_mul_f32_e32 v3, v16, v3
	v_mul_f32_e32 v3, v3, v12
	v_add_f32_e32 v4, 1.0, v4
	v_add_f32_e32 v6, 1.0, v6
	v_rcp_f32_e32 v4, v4
	v_rcp_f32_e32 v6, v6
	v_mul_f32_e32 v4, v17, v4
	v_mul_f32_e32 v6, v9, v6
	v_mul_f32_e32 v4, v4, v13
	v_mul_f32_e32 v5, v6, v5
	v_lshl_add_u64 v[6:7], v[166:167], 0, v[160:161]
	v_cvt_pk_bf16_f32 v3, v3, v4
	v_cvt_pk_bf16_f32 v4, v14, v11
	v_cvt_pk_bf16_f32 v5, v8, v5
	global_store_dwordx4 v[6:7], v[2:5], off
	s_cbranch_vccz .LBB0_105
	s_waitcnt vmcnt(0)
	v_readlane_b32 s50, v254, 28
	v_readlane_b32 s56, v254, 30
	v_readlane_b32 s60, v254, 39
	s_cmpk_gt_u32 s4, 0xff
	v_readlane_b32 s51, v254, 29
	v_readlane_b32 s57, v254, 31
	v_readlane_b32 s61, v254, 40
	s_mov_b64 s[58:59], s[84:85]
	s_cbranch_scc1 .LBB0_112
	s_barrier

.LBB0_182:
	s_add_u32 s26, s38, 0x4000
	s_addc_u32 s27, s39, 0
	s_cmpk_eq_i32 s61, 0x54
	s_cselect_b32 s48, s0, s26
	s_cselect_b32 s49, s1, s27
	s_cselect_b32 s26, s24, s59
	s_cselect_b32 s27, s25, s60
	s_add_u32 s42, s48, 0x8000
	s_addc_u32 s43, s49, 0
	s_add_i32 s62, 0, 0x10000
	v_add_u32_e32 v134, s62, v155
	ds_read_b128 v[148:151], v134
	ds_read_b128 v[158:161], v134 offset:1024
	ds_read_b128 v[162:165], v134 offset:2048
	ds_read_b128 v[180:183], v134 offset:3072
	s_add_i32 m0, s7, 0xc000
	ds_read_b128 v[184:187], v157
	ds_read_b128 v[188:191], v157 offset:1024
	ds_read_b128 v[192:195], v157 offset:2048
	ds_read_b128 v[196:199], v157 offset:3072
	ds_read_b128 v[200:203], v157 offset:4096
	ds_read_b128 v[204:207], v157 offset:5120
	ds_read_b128 v[208:211], v157 offset:6144
	ds_read_b128 v[212:215], v157 offset:7168
	global_load_lds_dwordx4 v144, s[38:39]
	s_add_i32 m0, s7, 0xe000
	s_nop 0
	global_load_lds_dwordx4 v146, s[38:39]
	s_waitcnt lgkmcnt(8)
	s_barrier
	s_waitcnt lgkmcnt(0)
	s_setprio 1
	s_waitcnt lgkmcnt(0)
	v_mfma_f32_16x16x32_bf16 v[126:129], v[148:151], v[184:187], v[126:129]
	v_mfma_f32_16x16x32_bf16 v[122:125], v[162:165], v[184:187], v[122:125]
	v_mfma_f32_16x16x32_bf16 v[110:113], v[148:151], v[192:195], v[110:113]
	v_mfma_f32_16x16x32_bf16 v[106:109], v[162:165], v[192:195], v[106:109]
	v_mfma_f32_16x16x32_bf16 v[94:97], v[148:151], v[200:203], v[94:97]
	v_mfma_f32_16x16x32_bf16 v[90:93], v[162:165], v[200:203], v[90:93]
	v_mfma_f32_16x16x32_bf16 v[78:81], v[148:151], v[208:211], v[78:81]
	v_mfma_f32_16x16x32_bf16 v[74:77], v[162:165], v[208:211], v[74:77]
	v_mfma_f32_16x16x32_bf16 v[126:129], v[158:161], v[188:191], v[126:129]
	v_mfma_f32_16x16x32_bf16 v[122:125], v[180:183], v[188:191], v[122:125]
	v_mfma_f32_16x16x32_bf16 v[110:113], v[158:161], v[196:199], v[110:113]
	v_mfma_f32_16x16x32_bf16 v[106:109], v[180:183], v[196:199], v[106:109]
	v_mfma_f32_16x16x32_bf16 v[94:97], v[158:161], v[204:207], v[94:97]
	v_mfma_f32_16x16x32_bf16 v[90:93], v[180:183], v[204:207], v[90:93]
	v_mfma_f32_16x16x32_bf16 v[78:81], v[158:161], v[212:215], v[78:81]
	v_mfma_f32_16x16x32_bf16 v[74:77], v[180:183], v[212:215], v[74:77]
	s_setprio 0
	s_barrier
	s_add_i32 s64, 0, 0x14000
	v_add_u32_e32 v134, s64, v155
	s_add_i32 s62, s62, s6
	ds_read_b128 v[216:219], v134
	ds_read_b128 v[220:223], v134 offset:1024
	ds_read_b128 v[224:227], v134 offset:2048
	ds_read_b128 v[228:231], v134 offset:3072
	s_mov_b32 m0, s62
	v_lshl_add_u64 v[152:153], s[26:27], 0, v[138:139]
	global_load_lds_dwordx4 v0, s[26:27]
	s_add_i32 m0, s62, 0x2000
	s_nop 0
	global_load_lds_dwordx4 v[152:153], off
	s_barrier
	s_waitcnt lgkmcnt(0)
	s_setprio 1
	s_waitcnt lgkmcnt(0)
	v_mfma_f32_16x16x32_bf16 v[118:121], v[216:219], v[184:187], v[118:121]
	v_mfma_f32_16x16x32_bf16 v[114:117], v[224:227], v[184:187], v[114:117]
	v_mfma_f32_16x16x32_bf16 v[102:105], v[216:219], v[192:195], v[102:105]
	v_mfma_f32_16x16x32_bf16 v[98:101], v[224:227], v[192:195], v[98:101]
	v_mfma_f32_16x16x32_bf16 v[86:89], v[216:219], v[200:203], v[86:89]
	v_mfma_f32_16x16x32_bf16 v[82:85], v[224:227], v[200:203], v[82:85]
	v_mfma_f32_16x16x32_bf16 v[70:73], v[216:219], v[208:211], v[70:73]
	v_mfma_f32_16x16x32_bf16 v[66:69], v[224:227], v[208:211], v[66:69]
	v_mfma_f32_16x16x32_bf16 v[118:121], v[220:223], v[188:191], v[118:121]
	v_mfma_f32_16x16x32_bf16 v[114:117], v[228:231], v[188:191], v[114:117]
	v_mfma_f32_16x16x32_bf16 v[102:105], v[220:223], v[196:199], v[102:105]
	v_mfma_f32_16x16x32_bf16 v[98:101], v[228:231], v[196:199], v[98:101]
	v_mfma_f32_16x16x32_bf16 v[86:89], v[220:223], v[204:207], v[86:89]
	v_mfma_f32_16x16x32_bf16 v[82:85], v[228:231], v[204:207], v[82:85]
	v_mfma_f32_16x16x32_bf16 v[70:73], v[220:223], v[212:215], v[70:73]
	v_mfma_f32_16x16x32_bf16 v[66:69], v[228:231], v[212:215], v[66:69]
	s_setprio 0
	s_mov_b32 m0, s7
	s_barrier
	ds_read_b128 v[184:187], v157 offset:16384
	ds_read_b128 v[188:191], v157 offset:17408
	ds_read_b128 v[192:195], v157 offset:18432
	ds_read_b128 v[196:199], v157 offset:19456
	ds_read_b128 v[200:203], v157 offset:20480
	ds_read_b128 v[204:207], v157 offset:21504
	ds_read_b128 v[208:211], v157 offset:22528
	ds_read_b128 v[212:215], v157 offset:23552
	global_load_lds_dwordx4 v142, s[48:49]
	s_mov_b32 m0, s14
	s_nop 0
	global_load_lds_dwordx4 v140, s[48:49]
	s_barrier
	s_waitcnt lgkmcnt(0)
	s_setprio 1
	s_waitcnt lgkmcnt(0)
	v_mfma_f32_16x16x32_bf16 v[62:65], v[148:151], v[184:187], v[62:65]
	v_mfma_f32_16x16x32_bf16 v[58:61], v[162:165], v[184:187], v[58:61]
	v_mfma_f32_16x16x32_bf16 v[46:49], v[148:151], v[192:195], v[46:49]
	v_mfma_f32_16x16x32_bf16 v[42:45], v[162:165], v[192:195], v[42:45]
	v_mfma_f32_16x16x32_bf16 v[30:33], v[148:151], v[200:203], v[30:33]
	v_mfma_f32_16x16x32_bf16 v[26:29], v[162:165], v[200:203], v[26:29]
	v_mfma_f32_16x16x32_bf16 v[14:17], v[148:151], v[208:211], v[14:17]
	v_mfma_f32_16x16x32_bf16 v[10:13], v[162:165], v[208:211], v[10:13]
	v_mfma_f32_16x16x32_bf16 v[62:65], v[158:161], v[188:191], v[62:65]
	v_mfma_f32_16x16x32_bf16 v[58:61], v[180:183], v[188:191], v[58:61]
	v_mfma_f32_16x16x32_bf16 v[46:49], v[158:161], v[196:199], v[46:49]
	v_mfma_f32_16x16x32_bf16 v[42:45], v[180:183], v[196:199], v[42:45]
	v_mfma_f32_16x16x32_bf16 v[30:33], v[158:161], v[204:207], v[30:33]
	v_mfma_f32_16x16x32_bf16 v[26:29], v[180:183], v[204:207], v[26:29]
	v_mfma_f32_16x16x32_bf16 v[14:17], v[158:161], v[212:215], v[14:17]
	v_mfma_f32_16x16x32_bf16 v[10:13], v[180:183], v[212:215], v[10:13]
	s_setprio 0
	s_barrier
	s_add_u32 s62, s26, 0x160000
	s_addc_u32 s63, s27, 0
	s_add_i32 s64, s64, s6
	s_mov_b32 m0, s64
	s_nop 0
	global_load_lds_dwordx4 v0, s[62:63]
	s_add_i32 m0, s64, 0x2000
	s_nop 0
	global_load_lds_dwordx4 v138, s[62:63]
	s_waitcnt vmcnt(6)
	s_barrier
	s_setprio 1
	v_mfma_f32_16x16x32_bf16 v[54:57], v[216:219], v[184:187], v[54:57]
	v_mfma_f32_16x16x32_bf16 v[50:53], v[224:227], v[184:187], v[50:53]
	v_mfma_f32_16x16x32_bf16 v[38:41], v[216:219], v[192:195], v[38:41]
	v_mfma_f32_16x16x32_bf16 v[34:37], v[224:227], v[192:195], v[34:37]
	v_mfma_f32_16x16x32_bf16 v[22:25], v[216:219], v[200:203], v[22:25]
	v_mfma_f32_16x16x32_bf16 v[18:21], v[224:227], v[200:203], v[18:21]
	v_mfma_f32_16x16x32_bf16 v[6:9], v[216:219], v[208:211], v[6:9]
	v_mfma_f32_16x16x32_bf16 v[2:5], v[224:227], v[208:211], v[2:5]
	v_mfma_f32_16x16x32_bf16 v[54:57], v[220:223], v[188:191], v[54:57]
	v_mfma_f32_16x16x32_bf16 v[50:53], v[228:231], v[188:191], v[50:53]
	v_mfma_f32_16x16x32_bf16 v[38:41], v[220:223], v[196:199], v[38:41]
	v_mfma_f32_16x16x32_bf16 v[34:37], v[228:231], v[196:199], v[34:37]
	v_mfma_f32_16x16x32_bf16 v[22:25], v[220:223], v[204:207], v[22:25]
	v_mfma_f32_16x16x32_bf16 v[18:21], v[228:231], v[204:207], v[18:21]
	v_mfma_f32_16x16x32_bf16 v[6:9], v[220:223], v[212:215], v[6:9]
	v_mfma_f32_16x16x32_bf16 v[2:5], v[228:231], v[212:215], v[2:5]
	s_setprio 0
	s_add_i32 s62, 0, 0x18000
	v_add_u32_e32 v166, s62, v155
	s_barrier
	ds_read_b128 v[148:151], v166
	ds_read_b128 v[158:161], v166 offset:1024
	ds_read_b128 v[162:165], v166 offset:2048
	ds_read_b128 v[180:183], v166 offset:3072
	s_add_u32 s48, s48, 0x4000
	s_addc_u32 s49, s49, 0
	s_mov_b32 m0, s50
	ds_read_b128 v[184:187], v157 offset:32768
	ds_read_b128 v[188:191], v157 offset:33792
	ds_read_b128 v[192:195], v157 offset:34816
	ds_read_b128 v[196:199], v157 offset:35840
	ds_read_b128 v[200:203], v157 offset:36864
	ds_read_b128 v[204:207], v157 offset:37888
	ds_read_b128 v[208:211], v157 offset:38912
	ds_read_b128 v[212:215], v157 offset:39936
	global_load_lds_dwordx4 v142, s[48:49]
	s_mov_b32 m0, s51
	s_nop 0
	global_load_lds_dwordx4 v140, s[48:49]
	s_waitcnt lgkmcnt(8)
	s_barrier
	s_waitcnt lgkmcnt(0)
	s_setprio 1
	s_waitcnt lgkmcnt(0)
	v_mfma_f32_16x16x32_bf16 v[126:129], v[148:151], v[184:187], v[126:129]
	v_mfma_f32_16x16x32_bf16 v[122:125], v[162:165], v[184:187], v[122:125]
	v_mfma_f32_16x16x32_bf16 v[110:113], v[148:151], v[192:195], v[110:113]
	v_mfma_f32_16x16x32_bf16 v[106:109], v[162:165], v[192:195], v[106:109]
	v_mfma_f32_16x16x32_bf16 v[94:97], v[148:151], v[200:203], v[94:97]
	v_mfma_f32_16x16x32_bf16 v[90:93], v[162:165], v[200:203], v[90:93]
	v_mfma_f32_16x16x32_bf16 v[78:81], v[148:151], v[208:211], v[78:81]
	v_mfma_f32_16x16x32_bf16 v[74:77], v[162:165], v[208:211], v[74:77]
	v_mfma_f32_16x16x32_bf16 v[126:129], v[158:161], v[188:191], v[126:129]
	v_mfma_f32_16x16x32_bf16 v[122:125], v[180:183], v[188:191], v[122:125]
	v_mfma_f32_16x16x32_bf16 v[110:113], v[158:161], v[196:199], v[110:113]
	v_mfma_f32_16x16x32_bf16 v[106:109], v[180:183], v[196:199], v[106:109]
	v_mfma_f32_16x16x32_bf16 v[94:97], v[158:161], v[204:207], v[94:97]
	v_mfma_f32_16x16x32_bf16 v[90:93], v[180:183], v[204:207], v[90:93]
	v_mfma_f32_16x16x32_bf16 v[78:81], v[158:161], v[212:215], v[78:81]
	v_mfma_f32_16x16x32_bf16 v[74:77], v[180:183], v[212:215], v[74:77]
	s_setprio 0
	s_barrier
	s_add_i32 s48, 0, 0x1c000
	s_add_i32 s49, s62, s6
	v_add_u32_e32 v166, s48, v155
	s_add_u32 s100, s26, s10
	s_addc_u32 s101, s27, s11
	s_mov_b32 m0, s49
	ds_read_b128 v[216:219], v166
	ds_read_b128 v[220:223], v166 offset:1024
	ds_read_b128 v[224:227], v166 offset:2048
	ds_read_b128 v[228:231], v166 offset:3072
	global_load_lds_dwordx4 v0, s[100:101]
	s_add_u32 s100, s26, s10
	s_addc_u32 s101, s27, s11
	s_add_i32 m0, s49, 0x2000
	s_nop 0
	global_load_lds_dwordx4 v138, s[100:101]
	s_barrier
	s_waitcnt lgkmcnt(0)
	s_setprio 1
	s_waitcnt lgkmcnt(0)
	v_mfma_f32_16x16x32_bf16 v[118:121], v[216:219], v[184:187], v[118:121]
	v_mfma_f32_16x16x32_bf16 v[114:117], v[224:227], v[184:187], v[114:117]
	v_mfma_f32_16x16x32_bf16 v[102:105], v[216:219], v[192:195], v[102:105]
	v_mfma_f32_16x16x32_bf16 v[98:101], v[224:227], v[192:195], v[98:101]
	v_mfma_f32_16x16x32_bf16 v[86:89], v[216:219], v[200:203], v[86:89]
	v_mfma_f32_16x16x32_bf16 v[82:85], v[224:227], v[200:203], v[82:85]
	v_mfma_f32_16x16x32_bf16 v[70:73], v[216:219], v[208:211], v[70:73]
	v_mfma_f32_16x16x32_bf16 v[66:69], v[224:227], v[208:211], v[66:69]
	v_mfma_f32_16x16x32_bf16 v[118:121], v[220:223], v[188:191], v[118:121]
	v_mfma_f32_16x16x32_bf16 v[114:117], v[228:231], v[188:191], v[114:117]
	v_mfma_f32_16x16x32_bf16 v[102:105], v[220:223], v[196:199], v[102:105]
	v_mfma_f32_16x16x32_bf16 v[98:101], v[228:231], v[196:199], v[98:101]
	v_mfma_f32_16x16x32_bf16 v[86:89], v[220:223], v[204:207], v[86:89]
	v_mfma_f32_16x16x32_bf16 v[82:85], v[228:231], v[204:207], v[82:85]
	v_mfma_f32_16x16x32_bf16 v[70:73], v[220:223], v[212:215], v[70:73]
	v_mfma_f32_16x16x32_bf16 v[66:69], v[228:231], v[212:215], v[66:69]
	s_setprio 0
	s_mov_b32 m0, s52
	s_barrier
	ds_read_b128 v[184:187], v157 offset:49152
	ds_read_b128 v[188:191], v157 offset:50176
	ds_read_b128 v[192:195], v157 offset:51200
	ds_read_b128 v[196:199], v157 offset:52224
	ds_read_b128 v[200:203], v157 offset:53248
	ds_read_b128 v[204:207], v157 offset:54272
	ds_read_b128 v[208:211], v157 offset:55296
	ds_read_b128 v[212:215], v157 offset:56320
	global_load_lds_dwordx4 v142, s[42:43]
	s_mov_b32 m0, s53
	s_nop 0
	global_load_lds_dwordx4 v140, s[42:43]
	s_barrier
	s_waitcnt lgkmcnt(0)
	s_setprio 1
	s_waitcnt lgkmcnt(0)
	v_mfma_f32_16x16x32_bf16 v[62:65], v[148:151], v[184:187], v[62:65]
	v_mfma_f32_16x16x32_bf16 v[58:61], v[162:165], v[184:187], v[58:61]
	v_mfma_f32_16x16x32_bf16 v[46:49], v[148:151], v[192:195], v[46:49]
	v_mfma_f32_16x16x32_bf16 v[42:45], v[162:165], v[192:195], v[42:45]
	v_mfma_f32_16x16x32_bf16 v[30:33], v[148:151], v[200:203], v[30:33]
	v_mfma_f32_16x16x32_bf16 v[26:29], v[162:165], v[200:203], v[26:29]
	v_mfma_f32_16x16x32_bf16 v[14:17], v[148:151], v[208:211], v[14:17]
	v_mfma_f32_16x16x32_bf16 v[10:13], v[162:165], v[208:211], v[10:13]
	v_mfma_f32_16x16x32_bf16 v[62:65], v[158:161], v[188:191], v[62:65]
	v_mfma_f32_16x16x32_bf16 v[58:61], v[180:183], v[188:191], v[58:61]
	v_mfma_f32_16x16x32_bf16 v[46:49], v[158:161], v[196:199], v[46:49]
	v_mfma_f32_16x16x32_bf16 v[42:45], v[180:183], v[196:199], v[42:45]
	v_mfma_f32_16x16x32_bf16 v[30:33], v[158:161], v[204:207], v[30:33]
	v_mfma_f32_16x16x32_bf16 v[26:29], v[180:183], v[204:207], v[26:29]
	v_mfma_f32_16x16x32_bf16 v[14:17], v[158:161], v[212:215], v[14:17]
	v_mfma_f32_16x16x32_bf16 v[10:13], v[180:183], v[212:215], v[10:13]
	s_setprio 0
	s_barrier
	s_add_u32 s26, s26, 0x160080
	s_addc_u32 s27, s27, 0
	s_add_i32 s42, s48, s6
	s_mov_b32 m0, s42
	s_nop 0
	global_load_lds_dwordx4 v0, s[26:27]
	s_add_i32 m0, s42, 0x2000
	s_nop 0
	global_load_lds_dwordx4 v138, s[26:27]
	s_waitcnt vmcnt(6)
	s_barrier
	s_setprio 1
	v_mfma_f32_16x16x32_bf16 v[54:57], v[216:219], v[184:187], v[54:57]
	v_mfma_f32_16x16x32_bf16 v[50:53], v[224:227], v[184:187], v[50:53]
	v_mfma_f32_16x16x32_bf16 v[38:41], v[216:219], v[192:195], v[38:41]
	v_mfma_f32_16x16x32_bf16 v[34:37], v[224:227], v[192:195], v[34:37]
	v_mfma_f32_16x16x32_bf16 v[22:25], v[216:219], v[200:203], v[22:25]
	v_mfma_f32_16x16x32_bf16 v[18:21], v[224:227], v[200:203], v[18:21]
	v_mfma_f32_16x16x32_bf16 v[6:9], v[216:219], v[208:211], v[6:9]
	v_mfma_f32_16x16x32_bf16 v[2:5], v[224:227], v[208:211], v[2:5]
	v_mfma_f32_16x16x32_bf16 v[54:57], v[220:223], v[188:191], v[54:57]
	v_mfma_f32_16x16x32_bf16 v[50:53], v[228:231], v[188:191], v[50:53]
	v_mfma_f32_16x16x32_bf16 v[38:41], v[220:223], v[196:199], v[38:41]
	v_mfma_f32_16x16x32_bf16 v[34:37], v[228:231], v[196:199], v[34:37]
	v_mfma_f32_16x16x32_bf16 v[22:25], v[220:223], v[204:207], v[22:25]
	v_mfma_f32_16x16x32_bf16 v[18:21], v[228:231], v[204:207], v[18:21]
	v_mfma_f32_16x16x32_bf16 v[6:9], v[220:223], v[212:215], v[6:9]
	v_mfma_f32_16x16x32_bf16 v[2:5], v[228:231], v[212:215], v[2:5]
	s_setprio 0
	s_add_i32 s61, s61, 2
	s_add_u32 s59, s59, 0x100
	s_addc_u32 s60, s60, 0
	s_add_u32 s38, s38, 0x10000
	s_addc_u32 s39, s39, 0
	s_cmpk_gt_u32 s61, 0x55
	s_barrier
	s_cbranch_scc0 .LBB0_182
	v_lshl_add_u32 v152, s58, 8, v154
	v_lshl_or_b32 v150, s57, 8, v156
	v_ashrrev_i32_e32 v153, 31, v152
	v_ashrrev_i32_e32 v151, 31, v150
	v_lshlrev_b64 v[134:135], 11, v[152:153]
	v_lshl_add_u64 v[134:135], v[134:135], 0, v[150:151]
	v_lshlrev_b64 v[148:149], 2, v[134:135]
	v_lshl_add_u64 v[134:135], s[22:23], 0, v[148:149]
	v_lshl_add_u64 v[158:159], s[76:77], 0, v[148:149]
	v_readlane_b32 s62, v254, 34
	v_readlane_b32 s64, v254, 36
	v_readlane_b32 s60, v254, 39
	s_and_b64 vcc, exec, s[40:41]
	s_mov_b32 s57, s55
	s_mov_b32 s58, s56
	s_mov_b64 s[38:39], s[0:1]
	v_readlane_b32 s63, v254, 35
	v_readlane_b32 s65, v254, 37
	v_readlane_b32 s61, v254, 40
	v_mov_b64_e32 v[162:163], v[134:135]
	v_mov_b64_e32 v[152:153], v[158:159]
	global_load_dwordx4 v[180:183], v[162:163], off
	global_load_dwordx4 v[184:187], v[162:163], off offset:16
	global_load_dwordx4 v[188:191], v[162:163], off offset:512
	global_load_dwordx4 v[192:195], v[162:163], off offset:528
	s_mov_b64 s[26:27], 0x20000
	v_lshl_add_u64 v[164:165], v[134:135], 0, s[26:27]
	v_lshl_add_u64 v[160:161], v[158:159], 0, s[26:27]
	global_load_dwordx4 v[196:199], v[164:165], off
	global_load_dwordx4 v[200:203], v[164:165], off offset:16
	global_load_dwordx4 v[204:207], v[164:165], off offset:512
	global_load_dwordx4 v[208:211], v[164:165], off offset:528
	s_mov_b64 s[26:27], 0x40000
	v_lshl_add_u64 v[150:151], v[134:135], 0, s[26:27]
	v_lshl_add_u64 v[148:149], v[158:159], 0, s[26:27]
	global_load_dwordx4 v[212:215], v[150:151], off
	global_load_dwordx4 v[216:219], v[150:151], off offset:16
	global_load_dwordx4 v[220:223], v[150:151], off offset:512
	global_load_dwordx4 v[224:227], v[150:151], off offset:528
	s_waitcnt vmcnt(8)
	v_pk_fma_f32 v[126:127], v[126:127], 0.5, v[180:181] op_sel_hi:[1,0,1]
	v_pk_fma_f32 v[128:129], v[128:129], 0.5, v[182:183] op_sel_hi:[1,0,1]
	v_pk_fma_f32 v[122:123], v[122:123], 0.5, v[184:185] op_sel_hi:[1,0,1]
	v_pk_fma_f32 v[124:125], v[124:125], 0.5, v[186:187] op_sel_hi:[1,0,1]
	v_pk_fma_f32 v[118:119], v[118:119], 0.5, v[188:189] op_sel_hi:[1,0,1]
	v_pk_fma_f32 v[120:121], v[120:121], 0.5, v[190:191] op_sel_hi:[1,0,1]
	v_pk_fma_f32 v[114:115], v[114:115], 0.5, v[192:193] op_sel_hi:[1,0,1]
	v_pk_fma_f32 v[116:117], v[116:117], 0.5, v[194:195] op_sel_hi:[1,0,1]
	global_store_dwordx4 v[152:153], v[126:129], off
	global_store_dwordx4 v[152:153], v[122:125], off offset:16
	global_store_dwordx4 v[152:153], v[118:121], off offset:512
	global_store_dwordx4 v[152:153], v[114:117], off offset:528
	s_mov_b64 s[26:27], 0x60000
	v_lshl_add_u64 v[228:229], v[134:135], 0, s[26:27]
	v_lshl_add_u64 v[230:231], v[158:159], 0, s[26:27]
	global_load_dwordx4 v[180:183], v[228:229], off
	global_load_dwordx4 v[184:187], v[228:229], off offset:16
	global_load_dwordx4 v[188:191], v[228:229], off offset:512
	global_load_dwordx4 v[192:195], v[228:229], off offset:528
	s_waitcnt vmcnt(12)
	v_pk_fma_f32 v[110:111], v[110:111], 0.5, v[196:197] op_sel_hi:[1,0,1]
	v_pk_fma_f32 v[112:113], v[112:113], 0.5, v[198:199] op_sel_hi:[1,0,1]
	v_pk_fma_f32 v[106:107], v[106:107], 0.5, v[200:201] op_sel_hi:[1,0,1]
	v_pk_fma_f32 v[108:109], v[108:109], 0.5, v[202:203] op_sel_hi:[1,0,1]
	v_pk_fma_f32 v[102:103], v[102:103], 0.5, v[204:205] op_sel_hi:[1,0,1]
	v_pk_fma_f32 v[104:105], v[104:105], 0.5, v[206:207] op_sel_hi:[1,0,1]
	v_pk_fma_f32 v[98:99], v[98:99], 0.5, v[208:209] op_sel_hi:[1,0,1]
	v_pk_fma_f32 v[100:101], v[100:101], 0.5, v[210:211] op_sel_hi:[1,0,1]
	global_store_dwordx4 v[160:161], v[110:113], off
	global_store_dwordx4 v[160:161], v[106:109], off offset:16
	global_store_dwordx4 v[160:161], v[102:105], off offset:512
	global_store_dwordx4 v[160:161], v[98:101], off offset:528
	s_mov_b64 s[26:27], 0x100000
	v_lshl_add_u64 v[162:163], v[134:135], 0, s[26:27]
	v_lshl_add_u64 v[152:153], v[158:159], 0, s[26:27]
	global_load_dwordx4 v[196:199], v[162:163], off
	global_load_dwordx4 v[200:203], v[162:163], off offset:16
	global_load_dwordx4 v[204:207], v[162:163], off offset:512
	global_load_dwordx4 v[208:211], v[162:163], off offset:528
	s_waitcnt vmcnt(16)
	v_pk_fma_f32 v[94:95], v[94:95], 0.5, v[212:213] op_sel_hi:[1,0,1]
	v_pk_fma_f32 v[96:97], v[96:97], 0.5, v[214:215] op_sel_hi:[1,0,1]
	v_pk_fma_f32 v[90:91], v[90:91], 0.5, v[216:217] op_sel_hi:[1,0,1]
	v_pk_fma_f32 v[92:93], v[92:93], 0.5, v[218:219] op_sel_hi:[1,0,1]
	v_pk_fma_f32 v[86:87], v[86:87], 0.5, v[220:221] op_sel_hi:[1,0,1]
	v_pk_fma_f32 v[88:89], v[88:89], 0.5, v[222:223] op_sel_hi:[1,0,1]
	v_pk_fma_f32 v[82:83], v[82:83], 0.5, v[224:225] op_sel_hi:[1,0,1]
	v_pk_fma_f32 v[84:85], v[84:85], 0.5, v[226:227] op_sel_hi:[1,0,1]
	global_store_dwordx4 v[148:149], v[94:97], off
	global_store_dwordx4 v[148:149], v[90:93], off offset:16
	global_store_dwordx4 v[148:149], v[86:89], off offset:512
	global_store_dwordx4 v[148:149], v[82:85], off offset:528
	s_mov_b64 s[26:27], 0x120000
	v_lshl_add_u64 v[164:165], v[134:135], 0, s[26:27]
	v_lshl_add_u64 v[160:161], v[158:159], 0, s[26:27]
	global_load_dwordx4 v[212:215], v[164:165], off
	global_load_dwordx4 v[216:219], v[164:165], off offset:16
	global_load_dwordx4 v[220:223], v[164:165], off offset:512
	global_load_dwordx4 v[224:227], v[164:165], off offset:528
	s_waitcnt vmcnt(16)
	v_pk_fma_f32 v[78:79], v[78:79], 0.5, v[180:181] op_sel_hi:[1,0,1]
	v_pk_fma_f32 v[80:81], v[80:81], 0.5, v[182:183] op_sel_hi:[1,0,1]
	v_pk_fma_f32 v[74:75], v[74:75], 0.5, v[184:185] op_sel_hi:[1,0,1]
	v_pk_fma_f32 v[76:77], v[76:77], 0.5, v[186:187] op_sel_hi:[1,0,1]
	v_pk_fma_f32 v[70:71], v[70:71], 0.5, v[188:189] op_sel_hi:[1,0,1]
	v_pk_fma_f32 v[72:73], v[72:73], 0.5, v[190:191] op_sel_hi:[1,0,1]
	v_pk_fma_f32 v[66:67], v[66:67], 0.5, v[192:193] op_sel_hi:[1,0,1]
	v_pk_fma_f32 v[68:69], v[68:69], 0.5, v[194:195] op_sel_hi:[1,0,1]
	global_store_dwordx4 v[230:231], v[78:81], off
	global_store_dwordx4 v[230:231], v[74:77], off offset:16
	global_store_dwordx4 v[230:231], v[70:73], off offset:512
	global_store_dwordx4 v[230:231], v[66:69], off offset:528
	s_mov_b64 s[26:27], 0x140000
	v_lshl_add_u64 v[150:151], v[134:135], 0, s[26:27]
	v_lshl_add_u64 v[148:149], v[158:159], 0, s[26:27]
	global_load_dwordx4 v[180:183], v[150:151], off
	global_load_dwordx4 v[184:187], v[150:151], off offset:16
	global_load_dwordx4 v[188:191], v[150:151], off offset:512
	global_load_dwordx4 v[192:195], v[150:151], off offset:528
	s_waitcnt vmcnt(16)
	v_pk_fma_f32 v[62:63], v[62:63], 0.5, v[196:197] op_sel_hi:[1,0,1]
	v_pk_fma_f32 v[64:65], v[64:65], 0.5, v[198:199] op_sel_hi:[1,0,1]
	v_pk_fma_f32 v[58:59], v[58:59], 0.5, v[200:201] op_sel_hi:[1,0,1]
	v_pk_fma_f32 v[60:61], v[60:61], 0.5, v[202:203] op_sel_hi:[1,0,1]
	v_pk_fma_f32 v[54:55], v[54:55], 0.5, v[204:205] op_sel_hi:[1,0,1]
	v_pk_fma_f32 v[56:57], v[56:57], 0.5, v[206:207] op_sel_hi:[1,0,1]
	v_pk_fma_f32 v[50:51], v[50:51], 0.5, v[208:209] op_sel_hi:[1,0,1]
	v_pk_fma_f32 v[52:53], v[52:53], 0.5, v[210:211] op_sel_hi:[1,0,1]
	global_store_dwordx4 v[152:153], v[62:65], off
	global_store_dwordx4 v[152:153], v[58:61], off offset:16
	global_store_dwordx4 v[152:153], v[54:57], off offset:512
	global_store_dwordx4 v[152:153], v[50:53], off offset:528
	s_mov_b64 s[26:27], 0x160000
	v_lshl_add_u64 v[228:229], v[134:135], 0, s[26:27]
	v_lshl_add_u64 v[230:231], v[158:159], 0, s[26:27]
	global_load_dwordx4 v[196:199], v[228:229], off
	global_load_dwordx4 v[200:203], v[228:229], off offset:16
	global_load_dwordx4 v[204:207], v[228:229], off offset:512
	global_load_dwordx4 v[208:211], v[228:229], off offset:528
	s_waitcnt vmcnt(16)
	v_pk_fma_f32 v[46:47], v[46:47], 0.5, v[212:213] op_sel_hi:[1,0,1]
	v_pk_fma_f32 v[48:49], v[48:49], 0.5, v[214:215] op_sel_hi:[1,0,1]
	v_pk_fma_f32 v[42:43], v[42:43], 0.5, v[216:217] op_sel_hi:[1,0,1]
	v_pk_fma_f32 v[44:45], v[44:45], 0.5, v[218:219] op_sel_hi:[1,0,1]
	v_pk_fma_f32 v[38:39], v[38:39], 0.5, v[220:221] op_sel_hi:[1,0,1]
	v_pk_fma_f32 v[40:41], v[40:41], 0.5, v[222:223] op_sel_hi:[1,0,1]
	v_pk_fma_f32 v[34:35], v[34:35], 0.5, v[224:225] op_sel_hi:[1,0,1]
	v_pk_fma_f32 v[36:37], v[36:37], 0.5, v[226:227] op_sel_hi:[1,0,1]
	global_store_dwordx4 v[160:161], v[46:49], off
	global_store_dwordx4 v[160:161], v[42:45], off offset:16
	global_store_dwordx4 v[160:161], v[38:41], off offset:512
	global_store_dwordx4 v[160:161], v[34:37], off offset:528
	s_waitcnt vmcnt(12)
	v_pk_fma_f32 v[30:31], v[30:31], 0.5, v[180:181] op_sel_hi:[1,0,1]
	v_pk_fma_f32 v[32:33], v[32:33], 0.5, v[182:183] op_sel_hi:[1,0,1]
	v_pk_fma_f32 v[26:27], v[26:27], 0.5, v[184:185] op_sel_hi:[1,0,1]
	v_pk_fma_f32 v[28:29], v[28:29], 0.5, v[186:187] op_sel_hi:[1,0,1]
	v_pk_fma_f32 v[22:23], v[22:23], 0.5, v[188:189] op_sel_hi:[1,0,1]
	v_pk_fma_f32 v[24:25], v[24:25], 0.5, v[190:191] op_sel_hi:[1,0,1]
	v_pk_fma_f32 v[18:19], v[18:19], 0.5, v[192:193] op_sel_hi:[1,0,1]
	v_pk_fma_f32 v[20:21], v[20:21], 0.5, v[194:195] op_sel_hi:[1,0,1]
	global_store_dwordx4 v[148:149], v[30:33], off
	global_store_dwordx4 v[148:149], v[26:29], off offset:16
	global_store_dwordx4 v[148:149], v[22:25], off offset:512
	global_store_dwordx4 v[148:149], v[18:21], off offset:528
	s_waitcnt vmcnt(8)
	v_pk_fma_f32 v[14:15], v[14:15], 0.5, v[196:197] op_sel_hi:[1,0,1]
	v_pk_fma_f32 v[16:17], v[16:17], 0.5, v[198:199] op_sel_hi:[1,0,1]
	v_pk_fma_f32 v[10:11], v[10:11], 0.5, v[200:201] op_sel_hi:[1,0,1]
	v_pk_fma_f32 v[12:13], v[12:13], 0.5, v[202:203] op_sel_hi:[1,0,1]
	v_pk_fma_f32 v[6:7], v[6:7], 0.5, v[204:205] op_sel_hi:[1,0,1]
	v_pk_fma_f32 v[8:9], v[8:9], 0.5, v[206:207] op_sel_hi:[1,0,1]
	v_pk_fma_f32 v[2:3], v[2:3], 0.5, v[208:209] op_sel_hi:[1,0,1]
	v_pk_fma_f32 v[4:5], v[4:5], 0.5, v[210:211] op_sel_hi:[1,0,1]
	global_store_dwordx4 v[230:231], v[14:17], off
	global_store_dwordx4 v[230:231], v[10:13], off offset:16
	global_store_dwordx4 v[230:231], v[6:9], off offset:512
	global_store_dwordx4 v[230:231], v[2:5], off offset:528
	s_mov_b64 s[26:27], s[24:25]
	s_cbranch_vccz .LBB0_171
	s_waitcnt vmcnt(0)
	v_readlane_b32 s52, v254, 26
	v_readlane_b32 s56, v254, 30
	v_readlane_b32 s54, v254, 32
	s_cmpk_gt_u32 s4, 0xff
	v_readlane_b32 s53, v254, 27
	v_readlane_b32 s57, v254, 31
	v_readlane_b32 s55, v254, 33
	s_mov_b64 s[58:59], s[84:85]
	s_cbranch_scc1 .LBB0_186
	s_barrier

.LBB0_360:
	s_add_u32 s26, s42, 0xfff80080
	s_addc_u32 s27, s43, -1
	s_add_i32 s58, 0, 0x10000
	v_add_u32_e32 v134, s58, v153
	ds_read_b128 v[148:151], v134
	ds_read_b128 v[156:159], v134 offset:1024
	ds_read_b128 v[160:163], v134 offset:2048
	ds_read_b128 v[164:167], v134 offset:3072
	s_cmp_eq_u32 s57, 28
	s_cselect_b32 s45, s23, s27
	s_cselect_b32 s44, s53, s26
	s_cselect_b32 s27, s1, s56
	s_cselect_b32 s26, s54, s55
	s_add_i32 m0, s7, 0xc000
	ds_read_b128 v[180:183], v155
	ds_read_b128 v[184:187], v155 offset:1024
	ds_read_b128 v[188:191], v155 offset:2048
	ds_read_b128 v[192:195], v155 offset:3072
	ds_read_b128 v[196:199], v155 offset:4096
	ds_read_b128 v[200:203], v155 offset:5120
	ds_read_b128 v[204:207], v155 offset:6144
	ds_read_b128 v[208:211], v155 offset:7168
	global_load_lds_dwordx4 v144, s[42:43]
	s_add_i32 m0, s7, 0xe000
	s_nop 0
	global_load_lds_dwordx4 v146, s[42:43]
	s_waitcnt lgkmcnt(8)
	s_barrier
	s_waitcnt lgkmcnt(0)
	s_setprio 1
	s_waitcnt lgkmcnt(0)
	v_mfma_f32_16x16x32_bf16 v[126:129], v[148:151], v[180:183], v[126:129]
	v_mfma_f32_16x16x32_bf16 v[122:125], v[160:163], v[180:183], v[122:125]
	v_mfma_f32_16x16x32_bf16 v[118:121], v[148:151], v[188:191], v[118:121]
	v_mfma_f32_16x16x32_bf16 v[110:113], v[160:163], v[188:191], v[110:113]
	v_mfma_f32_16x16x32_bf16 v[102:105], v[148:151], v[196:199], v[102:105]
	v_mfma_f32_16x16x32_bf16 v[94:97], v[160:163], v[196:199], v[94:97]
	v_mfma_f32_16x16x32_bf16 v[86:89], v[148:151], v[204:207], v[86:89]
	v_mfma_f32_16x16x32_bf16 v[78:81], v[160:163], v[204:207], v[78:81]
	v_mfma_f32_16x16x32_bf16 v[126:129], v[156:159], v[184:187], v[126:129]
	v_mfma_f32_16x16x32_bf16 v[122:125], v[164:167], v[184:187], v[122:125]
	v_mfma_f32_16x16x32_bf16 v[118:121], v[156:159], v[192:195], v[118:121]
	v_mfma_f32_16x16x32_bf16 v[110:113], v[164:167], v[192:195], v[110:113]
	v_mfma_f32_16x16x32_bf16 v[102:105], v[156:159], v[200:203], v[102:105]
	v_mfma_f32_16x16x32_bf16 v[94:97], v[164:167], v[200:203], v[94:97]
	v_mfma_f32_16x16x32_bf16 v[86:89], v[156:159], v[208:211], v[86:89]
	v_mfma_f32_16x16x32_bf16 v[78:81], v[164:167], v[208:211], v[78:81]
	s_setprio 0
	s_barrier
	s_add_i32 s60, 0, 0x14000
	v_add_u32_e32 v134, s60, v153
	s_add_i32 s58, s58, s6
	ds_read_b128 v[212:215], v134
	ds_read_b128 v[216:219], v134 offset:1024
	ds_read_b128 v[220:223], v134 offset:2048
	ds_read_b128 v[224:227], v134 offset:3072
	s_mov_b32 m0, s58
	v_lshl_add_u64 v[228:229], s[26:27], 0, v[138:139]
	global_load_lds_dwordx4 v0, s[26:27]
	s_add_i32 m0, s58, 0x2000
	s_nop 0
	global_load_lds_dwordx4 v[228:229], off
	s_barrier
	s_waitcnt lgkmcnt(0)
	s_setprio 1
	s_waitcnt lgkmcnt(0)
	v_mfma_f32_16x16x32_bf16 v[114:117], v[212:215], v[180:183], v[114:117]
	v_mfma_f32_16x16x32_bf16 v[106:109], v[220:223], v[180:183], v[106:109]
	v_mfma_f32_16x16x32_bf16 v[98:101], v[212:215], v[188:191], v[98:101]
	v_mfma_f32_16x16x32_bf16 v[90:93], v[220:223], v[188:191], v[90:93]
	v_mfma_f32_16x16x32_bf16 v[82:85], v[212:215], v[196:199], v[82:85]
	v_mfma_f32_16x16x32_bf16 v[74:77], v[220:223], v[196:199], v[74:77]
	v_mfma_f32_16x16x32_bf16 v[70:73], v[212:215], v[204:207], v[70:73]
	v_mfma_f32_16x16x32_bf16 v[66:69], v[220:223], v[204:207], v[66:69]
	v_mfma_f32_16x16x32_bf16 v[114:117], v[216:219], v[184:187], v[114:117]
	v_mfma_f32_16x16x32_bf16 v[106:109], v[224:227], v[184:187], v[106:109]
	v_mfma_f32_16x16x32_bf16 v[98:101], v[216:219], v[192:195], v[98:101]
	v_mfma_f32_16x16x32_bf16 v[90:93], v[224:227], v[192:195], v[90:93]
	v_mfma_f32_16x16x32_bf16 v[82:85], v[216:219], v[200:203], v[82:85]
	v_mfma_f32_16x16x32_bf16 v[74:77], v[224:227], v[200:203], v[74:77]
	v_mfma_f32_16x16x32_bf16 v[70:73], v[216:219], v[208:211], v[70:73]
	v_mfma_f32_16x16x32_bf16 v[66:69], v[224:227], v[208:211], v[66:69]
	s_setprio 0
	s_mov_b32 m0, s7
	v_lshl_add_u64 v[230:231], s[44:45], 0, v[142:143]
	s_barrier
	ds_read_b128 v[180:183], v155 offset:16384
	ds_read_b128 v[184:187], v155 offset:17408
	ds_read_b128 v[188:191], v155 offset:18432
	ds_read_b128 v[192:195], v155 offset:19456
	ds_read_b128 v[196:199], v155 offset:20480
	ds_read_b128 v[200:203], v155 offset:21504
	ds_read_b128 v[204:207], v155 offset:22528
	ds_read_b128 v[208:211], v155 offset:23552
	global_load_lds_dwordx4 v[230:231], off
	v_lshl_add_u64 v[232:233], s[44:45], 0, v[140:141]
	s_mov_b32 m0, s14
	s_nop 0
	global_load_lds_dwordx4 v[232:233], off
	s_barrier
	s_waitcnt lgkmcnt(0)
	s_setprio 1
	s_waitcnt lgkmcnt(0)
	v_mfma_f32_16x16x32_bf16 v[62:65], v[148:151], v[180:183], v[62:65]
	v_mfma_f32_16x16x32_bf16 v[58:61], v[160:163], v[180:183], v[58:61]
	v_mfma_f32_16x16x32_bf16 v[54:57], v[148:151], v[188:191], v[54:57]
	v_mfma_f32_16x16x32_bf16 v[46:49], v[160:163], v[188:191], v[46:49]
	v_mfma_f32_16x16x32_bf16 v[38:41], v[148:151], v[196:199], v[38:41]
	v_mfma_f32_16x16x32_bf16 v[30:33], v[160:163], v[196:199], v[30:33]
	v_mfma_f32_16x16x32_bf16 v[22:25], v[148:151], v[204:207], v[22:25]
	v_mfma_f32_16x16x32_bf16 v[14:17], v[160:163], v[204:207], v[14:17]
	v_mfma_f32_16x16x32_bf16 v[62:65], v[156:159], v[184:187], v[62:65]
	v_mfma_f32_16x16x32_bf16 v[58:61], v[164:167], v[184:187], v[58:61]
	v_mfma_f32_16x16x32_bf16 v[54:57], v[156:159], v[192:195], v[54:57]
	v_mfma_f32_16x16x32_bf16 v[46:49], v[164:167], v[192:195], v[46:49]
	v_mfma_f32_16x16x32_bf16 v[38:41], v[156:159], v[200:203], v[38:41]
	v_mfma_f32_16x16x32_bf16 v[30:33], v[164:167], v[200:203], v[30:33]
	v_mfma_f32_16x16x32_bf16 v[22:25], v[156:159], v[208:211], v[22:25]
	v_mfma_f32_16x16x32_bf16 v[14:17], v[164:167], v[208:211], v[14:17]
	s_setprio 0
	s_barrier
	s_add_u32 s58, s26, 0x80000
	s_addc_u32 s59, s27, 0
	s_add_i32 s60, s60, s6
	s_mov_b32 m0, s60
	s_nop 0
	global_load_lds_dwordx4 v0, s[58:59]
	s_add_i32 m0, s60, 0x2000
	s_nop 0
	global_load_lds_dwordx4 v138, s[58:59]
	s_waitcnt vmcnt(6)
	s_barrier
	s_setprio 1
	v_mfma_f32_16x16x32_bf16 v[50:53], v[212:215], v[180:183], v[50:53]
	v_mfma_f32_16x16x32_bf16 v[42:45], v[220:223], v[180:183], v[42:45]
	v_mfma_f32_16x16x32_bf16 v[34:37], v[212:215], v[188:191], v[34:37]
	v_mfma_f32_16x16x32_bf16 v[26:29], v[220:223], v[188:191], v[26:29]
	v_mfma_f32_16x16x32_bf16 v[18:21], v[212:215], v[196:199], v[18:21]
	v_mfma_f32_16x16x32_bf16 v[10:13], v[220:223], v[196:199], v[10:13]
	v_mfma_f32_16x16x32_bf16 v[6:9], v[212:215], v[204:207], v[6:9]
	v_mfma_f32_16x16x32_bf16 v[2:5], v[220:223], v[204:207], v[2:5]
	v_mfma_f32_16x16x32_bf16 v[50:53], v[216:219], v[184:187], v[50:53]
	v_mfma_f32_16x16x32_bf16 v[42:45], v[224:227], v[184:187], v[42:45]
	v_mfma_f32_16x16x32_bf16 v[34:37], v[216:219], v[192:195], v[34:37]
	v_mfma_f32_16x16x32_bf16 v[26:29], v[224:227], v[192:195], v[26:29]
	v_mfma_f32_16x16x32_bf16 v[18:21], v[216:219], v[200:203], v[18:21]
	v_mfma_f32_16x16x32_bf16 v[10:13], v[224:227], v[200:203], v[10:13]
	v_mfma_f32_16x16x32_bf16 v[6:9], v[216:219], v[208:211], v[6:9]
	v_mfma_f32_16x16x32_bf16 v[2:5], v[224:227], v[208:211], v[2:5]
	s_setprio 0
	s_add_i32 s58, 0, 0x18000
	v_add_u32_e32 v164, s58, v153
	s_barrier
	ds_read_b128 v[148:151], v164
	ds_read_b128 v[156:159], v164 offset:1024
	ds_read_b128 v[160:163], v164 offset:2048
	ds_read_b128 v[164:167], v164 offset:3072
	s_add_u32 s44, s44, 0x80000
	s_addc_u32 s45, s45, 0
	s_mov_b32 m0, s46
	ds_read_b128 v[180:183], v155 offset:32768
	ds_read_b128 v[184:187], v155 offset:33792
	ds_read_b128 v[188:191], v155 offset:34816
	ds_read_b128 v[192:195], v155 offset:35840
	ds_read_b128 v[196:199], v155 offset:36864
	ds_read_b128 v[200:203], v155 offset:37888
	ds_read_b128 v[204:207], v155 offset:38912
	ds_read_b128 v[208:211], v155 offset:39936
	global_load_lds_dwordx4 v142, s[44:45]
	s_mov_b32 m0, s47
	s_nop 0
	global_load_lds_dwordx4 v140, s[44:45]
	s_waitcnt lgkmcnt(8)
	s_barrier
	s_waitcnt lgkmcnt(0)
	s_setprio 1
	s_waitcnt lgkmcnt(0)
	v_mfma_f32_16x16x32_bf16 v[126:129], v[148:151], v[180:183], v[126:129]
	v_mfma_f32_16x16x32_bf16 v[122:125], v[160:163], v[180:183], v[122:125]
	v_mfma_f32_16x16x32_bf16 v[118:121], v[148:151], v[188:191], v[118:121]
	v_mfma_f32_16x16x32_bf16 v[110:113], v[160:163], v[188:191], v[110:113]
	v_mfma_f32_16x16x32_bf16 v[102:105], v[148:151], v[196:199], v[102:105]
	v_mfma_f32_16x16x32_bf16 v[94:97], v[160:163], v[196:199], v[94:97]
	v_mfma_f32_16x16x32_bf16 v[86:89], v[148:151], v[204:207], v[86:89]
	v_mfma_f32_16x16x32_bf16 v[78:81], v[160:163], v[204:207], v[78:81]
	v_mfma_f32_16x16x32_bf16 v[126:129], v[156:159], v[184:187], v[126:129]
	v_mfma_f32_16x16x32_bf16 v[122:125], v[164:167], v[184:187], v[122:125]
	v_mfma_f32_16x16x32_bf16 v[118:121], v[156:159], v[192:195], v[118:121]
	v_mfma_f32_16x16x32_bf16 v[110:113], v[164:167], v[192:195], v[110:113]
	v_mfma_f32_16x16x32_bf16 v[102:105], v[156:159], v[200:203], v[102:105]
	v_mfma_f32_16x16x32_bf16 v[94:97], v[164:167], v[200:203], v[94:97]
	v_mfma_f32_16x16x32_bf16 v[86:89], v[156:159], v[208:211], v[86:89]
	v_mfma_f32_16x16x32_bf16 v[78:81], v[164:167], v[208:211], v[78:81]
	s_setprio 0
	s_barrier
	s_add_i32 s44, 0, 0x1c000
	s_add_i32 s45, s58, s6
	v_add_u32_e32 v224, s44, v153
	s_add_u32 s100, s26, s10
	s_addc_u32 s101, s27, s11
	s_mov_b32 m0, s45
	ds_read_b128 v[212:215], v224
	ds_read_b128 v[216:219], v224 offset:1024
	ds_read_b128 v[220:223], v224 offset:2048
	ds_read_b128 v[224:227], v224 offset:3072
	global_load_lds_dwordx4 v0, s[100:101]
	s_add_u32 s100, s26, s10
	s_addc_u32 s101, s27, s11
	s_add_i32 m0, s45, 0x2000
	s_nop 0
	global_load_lds_dwordx4 v138, s[100:101]
	s_barrier
	s_waitcnt lgkmcnt(0)
	s_setprio 1
	s_waitcnt lgkmcnt(0)
	v_mfma_f32_16x16x32_bf16 v[114:117], v[212:215], v[180:183], v[114:117]
	v_mfma_f32_16x16x32_bf16 v[106:109], v[220:223], v[180:183], v[106:109]
	v_mfma_f32_16x16x32_bf16 v[98:101], v[212:215], v[188:191], v[98:101]
	v_mfma_f32_16x16x32_bf16 v[90:93], v[220:223], v[188:191], v[90:93]
	v_mfma_f32_16x16x32_bf16 v[82:85], v[212:215], v[196:199], v[82:85]
	v_mfma_f32_16x16x32_bf16 v[74:77], v[220:223], v[196:199], v[74:77]
	v_mfma_f32_16x16x32_bf16 v[70:73], v[212:215], v[204:207], v[70:73]
	v_mfma_f32_16x16x32_bf16 v[66:69], v[220:223], v[204:207], v[66:69]
	v_mfma_f32_16x16x32_bf16 v[114:117], v[216:219], v[184:187], v[114:117]
	v_mfma_f32_16x16x32_bf16 v[106:109], v[224:227], v[184:187], v[106:109]
	v_mfma_f32_16x16x32_bf16 v[98:101], v[216:219], v[192:195], v[98:101]
	v_mfma_f32_16x16x32_bf16 v[90:93], v[224:227], v[192:195], v[90:93]
	v_mfma_f32_16x16x32_bf16 v[82:85], v[216:219], v[200:203], v[82:85]
	v_mfma_f32_16x16x32_bf16 v[74:77], v[224:227], v[200:203], v[74:77]
	v_mfma_f32_16x16x32_bf16 v[70:73], v[216:219], v[208:211], v[70:73]
	v_mfma_f32_16x16x32_bf16 v[66:69], v[224:227], v[208:211], v[66:69]
	s_setprio 0
	s_mov_b32 m0, s48
	v_lshl_add_u64 v[134:135], v[230:231], 0, s[10:11]
	s_barrier
	ds_read_b128 v[180:183], v155 offset:49152
	ds_read_b128 v[184:187], v155 offset:50176
	ds_read_b128 v[188:191], v155 offset:51200
	ds_read_b128 v[192:195], v155 offset:52224
	ds_read_b128 v[196:199], v155 offset:53248
	ds_read_b128 v[200:203], v155 offset:54272
	ds_read_b128 v[204:207], v155 offset:55296
	ds_read_b128 v[208:211], v155 offset:56320
	global_load_lds_dwordx4 v[134:135], off
	v_lshl_add_u64 v[134:135], v[232:233], 0, s[10:11]
	s_mov_b32 m0, s49
	s_nop 0
	global_load_lds_dwordx4 v[134:135], off
	s_barrier
	s_waitcnt lgkmcnt(0)
	s_setprio 1
	s_waitcnt lgkmcnt(0)
	v_mfma_f32_16x16x32_bf16 v[62:65], v[148:151], v[180:183], v[62:65]
	v_mfma_f32_16x16x32_bf16 v[58:61], v[160:163], v[180:183], v[58:61]
	v_mfma_f32_16x16x32_bf16 v[54:57], v[148:151], v[188:191], v[54:57]
	v_mfma_f32_16x16x32_bf16 v[46:49], v[160:163], v[188:191], v[46:49]
	v_mfma_f32_16x16x32_bf16 v[38:41], v[148:151], v[196:199], v[38:41]
	v_mfma_f32_16x16x32_bf16 v[30:33], v[160:163], v[196:199], v[30:33]
	v_mfma_f32_16x16x32_bf16 v[22:25], v[148:151], v[204:207], v[22:25]
	v_mfma_f32_16x16x32_bf16 v[14:17], v[160:163], v[204:207], v[14:17]
	v_mfma_f32_16x16x32_bf16 v[62:65], v[156:159], v[184:187], v[62:65]
	v_mfma_f32_16x16x32_bf16 v[58:61], v[164:167], v[184:187], v[58:61]
	v_mfma_f32_16x16x32_bf16 v[54:57], v[156:159], v[192:195], v[54:57]
	v_mfma_f32_16x16x32_bf16 v[46:49], v[164:167], v[192:195], v[46:49]
	v_mfma_f32_16x16x32_bf16 v[38:41], v[156:159], v[200:203], v[38:41]
	v_mfma_f32_16x16x32_bf16 v[30:33], v[164:167], v[200:203], v[30:33]
	v_mfma_f32_16x16x32_bf16 v[22:25], v[156:159], v[208:211], v[22:25]
	v_mfma_f32_16x16x32_bf16 v[14:17], v[164:167], v[208:211], v[14:17]
	s_setprio 0
	s_barrier
	s_add_u32 s26, s26, 0x80080
	s_addc_u32 s27, s27, 0
	s_add_i32 s44, s44, s6
	s_mov_b32 m0, s44
	s_nop 0
	global_load_lds_dwordx4 v0, s[26:27]
	s_add_i32 m0, s44, 0x2000
	s_nop 0
	global_load_lds_dwordx4 v138, s[26:27]
	s_waitcnt vmcnt(6)
	s_barrier
	s_setprio 1
	v_mfma_f32_16x16x32_bf16 v[50:53], v[212:215], v[180:183], v[50:53]
	v_mfma_f32_16x16x32_bf16 v[42:45], v[220:223], v[180:183], v[42:45]
	v_mfma_f32_16x16x32_bf16 v[34:37], v[212:215], v[188:191], v[34:37]
	v_mfma_f32_16x16x32_bf16 v[26:29], v[220:223], v[188:191], v[26:29]
	v_mfma_f32_16x16x32_bf16 v[18:21], v[212:215], v[196:199], v[18:21]
	v_mfma_f32_16x16x32_bf16 v[10:13], v[220:223], v[196:199], v[10:13]
	v_mfma_f32_16x16x32_bf16 v[6:9], v[212:215], v[204:207], v[6:9]
	v_mfma_f32_16x16x32_bf16 v[2:5], v[220:223], v[204:207], v[2:5]
	v_mfma_f32_16x16x32_bf16 v[50:53], v[216:219], v[184:187], v[50:53]
	v_mfma_f32_16x16x32_bf16 v[42:45], v[224:227], v[184:187], v[42:45]
	v_mfma_f32_16x16x32_bf16 v[34:37], v[216:219], v[192:195], v[34:37]
	v_mfma_f32_16x16x32_bf16 v[26:29], v[224:227], v[192:195], v[26:29]
	v_mfma_f32_16x16x32_bf16 v[18:21], v[216:219], v[200:203], v[18:21]
	v_mfma_f32_16x16x32_bf16 v[10:13], v[224:227], v[200:203], v[10:13]
	v_mfma_f32_16x16x32_bf16 v[6:9], v[216:219], v[208:211], v[6:9]
	v_mfma_f32_16x16x32_bf16 v[2:5], v[224:227], v[208:211], v[2:5]
	s_setprio 0
	s_add_i32 s57, s57, 2
	s_add_u32 s42, s42, 0x100
	s_addc_u32 s43, s43, 0
	s_add_u32 s55, s55, 0x100
	s_addc_u32 s56, s56, 0
	s_cmp_gt_u32 s57, 29
	s_barrier
	s_cbranch_scc0 .LBB0_360
	v_lshl_or_b32 v134, s51, 8, v154
	v_lshl_add_u32 v158, s52, 8, v152
	v_ashrrev_i32_e32 v135, 31, v134
	v_mov_b64_e32 v[148:149], s[88:89]
	v_mad_i64_i32 v[156:157], s[26:27], v158, s35, v[148:149]
	v_lshlrev_b64 v[150:151], 1, v[134:135]
	v_lshl_add_u64 v[134:135], v[156:157], 0, v[150:151]
	v_cvt_pk_bf16_f32 v126, v126, v127
	v_cvt_pk_bf16_f32 v127, v128, v129
	v_cvt_pk_bf16_f32 v128, v122, v123
	v_cvt_pk_bf16_f32 v129, v124, v125
	global_store_dwordx4 v[134:135], v[126:129], off
	v_cvt_pk_bf16_f32 v114, v114, v115
	v_cvt_pk_bf16_f32 v115, v116, v117
	v_cvt_pk_bf16_f32 v116, v106, v107
	v_or_b32_e32 v106, 16, v158
	v_mad_i64_i32 v[106:107], s[26:27], v106, s35, v[148:149]
	v_cvt_pk_bf16_f32 v117, v108, v109
	global_store_dwordx4 v[134:135], v[114:117], off offset:256
	s_and_b64 vcc, exec, s[40:41]
	s_mov_b32 s51, s0
	v_lshl_add_u64 v[114:115], v[106:107], 0, v[150:151]
	v_cvt_pk_bf16_f32 v106, v118, v119
	v_cvt_pk_bf16_f32 v107, v120, v121
	v_cvt_pk_bf16_f32 v108, v110, v111
	v_cvt_pk_bf16_f32 v109, v112, v113
	global_store_dwordx4 v[114:115], v[106:109], off
	v_cvt_pk_bf16_f32 v98, v98, v99
	v_cvt_pk_bf16_f32 v99, v100, v101
	v_cvt_pk_bf16_f32 v100, v90, v91
	v_or_b32_e32 v90, 32, v158
	v_mad_i64_i32 v[90:91], s[26:27], v90, s35, v[148:149]
	v_cvt_pk_bf16_f32 v101, v92, v93
	global_store_dwordx4 v[114:115], v[98:101], off offset:256
	s_mov_b32 s52, s22
	s_mov_b64 s[42:43], s[24:25]
	v_lshl_add_u64 v[98:99], v[90:91], 0, v[150:151]
	v_cvt_pk_bf16_f32 v90, v102, v103
	v_cvt_pk_bf16_f32 v91, v104, v105
	v_cvt_pk_bf16_f32 v92, v94, v95
	v_cvt_pk_bf16_f32 v93, v96, v97
	global_store_dwordx4 v[98:99], v[90:93], off
	v_cvt_pk_bf16_f32 v82, v82, v83
	v_cvt_pk_bf16_f32 v83, v84, v85
	v_cvt_pk_bf16_f32 v84, v74, v75
	v_or_b32_e32 v74, 48, v158
	v_mad_i64_i32 v[74:75], s[26:27], v74, s35, v[148:149]
	v_cvt_pk_bf16_f32 v85, v76, v77
	global_store_dwordx4 v[98:99], v[82:85], off offset:256
	s_nop 1
	v_lshl_add_u64 v[82:83], v[74:75], 0, v[150:151]
	v_cvt_pk_bf16_f32 v74, v86, v87
	v_cvt_pk_bf16_f32 v75, v88, v89
	v_cvt_pk_bf16_f32 v76, v78, v79
	v_cvt_pk_bf16_f32 v77, v80, v81
	global_store_dwordx4 v[82:83], v[74:77], off
	v_cvt_pk_bf16_f32 v70, v70, v71
	v_cvt_pk_bf16_f32 v71, v72, v73
	v_cvt_pk_bf16_f32 v72, v66, v67
	v_add_u32_e32 v66, 0x80, v158
	v_mad_i64_i32 v[66:67], s[26:27], v66, s35, v[148:149]
	v_lshl_add_u64 v[66:67], v[66:67], 0, v[150:151]
	v_cvt_pk_bf16_f32 v73, v68, v69
	global_store_dwordx4 v[82:83], v[70:73], off offset:256
	v_cvt_pk_bf16_f32 v62, v62, v63
	v_cvt_pk_bf16_f32 v63, v64, v65
	v_cvt_pk_bf16_f32 v64, v58, v59
	v_cvt_pk_bf16_f32 v65, v60, v61
	global_store_dwordx4 v[66:67], v[62:65], off
	v_cvt_pk_bf16_f32 v50, v50, v51
	v_cvt_pk_bf16_f32 v51, v52, v53
	v_cvt_pk_bf16_f32 v52, v42, v43
	v_add_u32_e32 v42, 0x90, v158
	v_mad_i64_i32 v[42:43], s[26:27], v42, s35, v[148:149]
	v_cvt_pk_bf16_f32 v53, v44, v45
	global_store_dwordx4 v[66:67], v[50:53], off offset:256
	s_nop 1
	v_lshl_add_u64 v[50:51], v[42:43], 0, v[150:151]
	v_cvt_pk_bf16_f32 v42, v54, v55
	v_cvt_pk_bf16_f32 v43, v56, v57
	v_cvt_pk_bf16_f32 v44, v46, v47
	v_cvt_pk_bf16_f32 v45, v48, v49
	global_store_dwordx4 v[50:51], v[42:45], off
	v_cvt_pk_bf16_f32 v34, v34, v35
	v_cvt_pk_bf16_f32 v35, v36, v37
	v_cvt_pk_bf16_f32 v36, v26, v27
	v_add_u32_e32 v26, 0xa0, v158
	v_mad_i64_i32 v[26:27], s[26:27], v26, s35, v[148:149]
	v_cvt_pk_bf16_f32 v37, v28, v29
	global_store_dwordx4 v[50:51], v[34:37], off offset:256
	s_nop 1
	v_lshl_add_u64 v[34:35], v[26:27], 0, v[150:151]
	v_cvt_pk_bf16_f32 v26, v38, v39
	v_cvt_pk_bf16_f32 v27, v40, v41
	v_cvt_pk_bf16_f32 v28, v30, v31
	v_cvt_pk_bf16_f32 v29, v32, v33
	global_store_dwordx4 v[34:35], v[26:29], off
	v_cvt_pk_bf16_f32 v18, v18, v19
	v_cvt_pk_bf16_f32 v19, v20, v21
	v_cvt_pk_bf16_f32 v20, v10, v11
	v_add_u32_e32 v10, 0xb0, v158
	v_mad_i64_i32 v[10:11], s[26:27], v10, s35, v[148:149]
	v_cvt_pk_bf16_f32 v21, v12, v13
	global_store_dwordx4 v[34:35], v[18:21], off offset:256
	s_mov_b64 s[26:27], s[38:39]
	s_nop 0
	v_lshl_add_u64 v[18:19], v[10:11], 0, v[150:151]
	v_cvt_pk_bf16_f32 v10, v22, v23
	v_cvt_pk_bf16_f32 v11, v24, v25
	v_cvt_pk_bf16_f32 v12, v14, v15
	v_cvt_pk_bf16_f32 v13, v16, v17
	global_store_dwordx4 v[18:19], v[10:13], off
	v_cvt_pk_bf16_f32 v6, v6, v7
	v_cvt_pk_bf16_f32 v7, v8, v9
	v_cvt_pk_bf16_f32 v8, v2, v3
	v_cvt_pk_bf16_f32 v9, v4, v5
	global_store_dwordx4 v[18:19], v[6:9], off offset:256
	s_cbranch_vccz .LBB0_357
	s_waitcnt vmcnt(0)
	v_readlane_b32 s52, v254, 26
	v_readlane_b32 s50, v254, 28
	s_cmpk_gt_u32 s4, 0xff
	v_readlane_b32 s53, v254, 27
	v_readlane_b32 s51, v254, 29
	s_cbranch_scc1 .LBB0_364
	s_barrier

.LBB0_627:
	s_add_u32 s26, s42, 0xfff80080
	s_addc_u32 s27, s43, -1
	s_add_i32 s58, 0, 0x10000
	v_add_u32_e32 v134, s58, v153
	ds_read_b128 v[148:151], v134
	ds_read_b128 v[156:159], v134 offset:1024
	ds_read_b128 v[160:163], v134 offset:2048
	ds_read_b128 v[164:167], v134 offset:3072
	s_cmp_eq_u32 s57, 28
	s_cselect_b32 s45, s23, s27
	s_cselect_b32 s44, s53, s26
	s_cselect_b32 s27, s1, s56
	s_cselect_b32 s26, s54, s55
	s_add_i32 m0, s7, 0xc000
	ds_read_b128 v[180:183], v155
	ds_read_b128 v[184:187], v155 offset:1024
	ds_read_b128 v[188:191], v155 offset:2048
	ds_read_b128 v[192:195], v155 offset:3072
	ds_read_b128 v[196:199], v155 offset:4096
	ds_read_b128 v[200:203], v155 offset:5120
	ds_read_b128 v[204:207], v155 offset:6144
	ds_read_b128 v[208:211], v155 offset:7168
	global_load_lds_dwordx4 v144, s[42:43]
	s_add_i32 m0, s7, 0xe000
	s_nop 0
	global_load_lds_dwordx4 v146, s[42:43]
	s_waitcnt lgkmcnt(8)
	s_barrier
	s_waitcnt lgkmcnt(0)
	s_setprio 1
	s_waitcnt lgkmcnt(0)
	v_mfma_f32_16x16x32_bf16 v[126:129], v[148:151], v[180:183], v[126:129]
	v_mfma_f32_16x16x32_bf16 v[122:125], v[160:163], v[180:183], v[122:125]
	v_mfma_f32_16x16x32_bf16 v[118:121], v[148:151], v[188:191], v[118:121]
	v_mfma_f32_16x16x32_bf16 v[110:113], v[160:163], v[188:191], v[110:113]
	v_mfma_f32_16x16x32_bf16 v[102:105], v[148:151], v[196:199], v[102:105]
	v_mfma_f32_16x16x32_bf16 v[94:97], v[160:163], v[196:199], v[94:97]
	v_mfma_f32_16x16x32_bf16 v[86:89], v[148:151], v[204:207], v[86:89]
	v_mfma_f32_16x16x32_bf16 v[78:81], v[160:163], v[204:207], v[78:81]
	v_mfma_f32_16x16x32_bf16 v[126:129], v[156:159], v[184:187], v[126:129]
	v_mfma_f32_16x16x32_bf16 v[122:125], v[164:167], v[184:187], v[122:125]
	v_mfma_f32_16x16x32_bf16 v[118:121], v[156:159], v[192:195], v[118:121]
	v_mfma_f32_16x16x32_bf16 v[110:113], v[164:167], v[192:195], v[110:113]
	v_mfma_f32_16x16x32_bf16 v[102:105], v[156:159], v[200:203], v[102:105]
	v_mfma_f32_16x16x32_bf16 v[94:97], v[164:167], v[200:203], v[94:97]
	v_mfma_f32_16x16x32_bf16 v[86:89], v[156:159], v[208:211], v[86:89]
	v_mfma_f32_16x16x32_bf16 v[78:81], v[164:167], v[208:211], v[78:81]
	s_setprio 0
	s_barrier
	s_add_i32 s60, 0, 0x14000
	v_add_u32_e32 v134, s60, v153
	s_add_i32 s58, s58, s6
	ds_read_b128 v[212:215], v134
	ds_read_b128 v[216:219], v134 offset:1024
	ds_read_b128 v[220:223], v134 offset:2048
	ds_read_b128 v[224:227], v134 offset:3072
	s_mov_b32 m0, s58
	v_lshl_add_u64 v[228:229], s[26:27], 0, v[138:139]
	global_load_lds_dwordx4 v0, s[26:27]
	s_add_i32 m0, s58, 0x2000
	s_nop 0
	global_load_lds_dwordx4 v[228:229], off
	s_barrier
	s_waitcnt lgkmcnt(0)
	s_setprio 1
	s_waitcnt lgkmcnt(0)
	v_mfma_f32_16x16x32_bf16 v[114:117], v[212:215], v[180:183], v[114:117]
	v_mfma_f32_16x16x32_bf16 v[106:109], v[220:223], v[180:183], v[106:109]
	v_mfma_f32_16x16x32_bf16 v[98:101], v[212:215], v[188:191], v[98:101]
	v_mfma_f32_16x16x32_bf16 v[90:93], v[220:223], v[188:191], v[90:93]
	v_mfma_f32_16x16x32_bf16 v[82:85], v[212:215], v[196:199], v[82:85]
	v_mfma_f32_16x16x32_bf16 v[74:77], v[220:223], v[196:199], v[74:77]
	v_mfma_f32_16x16x32_bf16 v[70:73], v[212:215], v[204:207], v[70:73]
	v_mfma_f32_16x16x32_bf16 v[66:69], v[220:223], v[204:207], v[66:69]
	v_mfma_f32_16x16x32_bf16 v[114:117], v[216:219], v[184:187], v[114:117]
	v_mfma_f32_16x16x32_bf16 v[106:109], v[224:227], v[184:187], v[106:109]
	v_mfma_f32_16x16x32_bf16 v[98:101], v[216:219], v[192:195], v[98:101]
	v_mfma_f32_16x16x32_bf16 v[90:93], v[224:227], v[192:195], v[90:93]
	v_mfma_f32_16x16x32_bf16 v[82:85], v[216:219], v[200:203], v[82:85]
	v_mfma_f32_16x16x32_bf16 v[74:77], v[224:227], v[200:203], v[74:77]
	v_mfma_f32_16x16x32_bf16 v[70:73], v[216:219], v[208:211], v[70:73]
	v_mfma_f32_16x16x32_bf16 v[66:69], v[224:227], v[208:211], v[66:69]
	s_setprio 0
	s_mov_b32 m0, s7
	v_lshl_add_u64 v[230:231], s[44:45], 0, v[142:143]
	s_barrier
	ds_read_b128 v[180:183], v155 offset:16384
	ds_read_b128 v[184:187], v155 offset:17408
	ds_read_b128 v[188:191], v155 offset:18432
	ds_read_b128 v[192:195], v155 offset:19456
	ds_read_b128 v[196:199], v155 offset:20480
	ds_read_b128 v[200:203], v155 offset:21504
	ds_read_b128 v[204:207], v155 offset:22528
	ds_read_b128 v[208:211], v155 offset:23552
	global_load_lds_dwordx4 v[230:231], off
	v_lshl_add_u64 v[232:233], s[44:45], 0, v[140:141]
	s_mov_b32 m0, s14
	s_nop 0
	global_load_lds_dwordx4 v[232:233], off
	s_barrier
	s_waitcnt lgkmcnt(0)
	s_setprio 1
	s_waitcnt lgkmcnt(0)
	v_mfma_f32_16x16x32_bf16 v[62:65], v[148:151], v[180:183], v[62:65]
	v_mfma_f32_16x16x32_bf16 v[58:61], v[160:163], v[180:183], v[58:61]
	v_mfma_f32_16x16x32_bf16 v[54:57], v[148:151], v[188:191], v[54:57]
	v_mfma_f32_16x16x32_bf16 v[46:49], v[160:163], v[188:191], v[46:49]
	v_mfma_f32_16x16x32_bf16 v[38:41], v[148:151], v[196:199], v[38:41]
	v_mfma_f32_16x16x32_bf16 v[30:33], v[160:163], v[196:199], v[30:33]
	v_mfma_f32_16x16x32_bf16 v[22:25], v[148:151], v[204:207], v[22:25]
	v_mfma_f32_16x16x32_bf16 v[14:17], v[160:163], v[204:207], v[14:17]
	v_mfma_f32_16x16x32_bf16 v[62:65], v[156:159], v[184:187], v[62:65]
	v_mfma_f32_16x16x32_bf16 v[58:61], v[164:167], v[184:187], v[58:61]
	v_mfma_f32_16x16x32_bf16 v[54:57], v[156:159], v[192:195], v[54:57]
	v_mfma_f32_16x16x32_bf16 v[46:49], v[164:167], v[192:195], v[46:49]
	v_mfma_f32_16x16x32_bf16 v[38:41], v[156:159], v[200:203], v[38:41]
	v_mfma_f32_16x16x32_bf16 v[30:33], v[164:167], v[200:203], v[30:33]
	v_mfma_f32_16x16x32_bf16 v[22:25], v[156:159], v[208:211], v[22:25]
	v_mfma_f32_16x16x32_bf16 v[14:17], v[164:167], v[208:211], v[14:17]
	s_setprio 0
	s_barrier
	s_add_u32 s58, s26, 0x80000
	s_addc_u32 s59, s27, 0
	s_add_i32 s60, s60, s6
	s_mov_b32 m0, s60
	s_nop 0
	global_load_lds_dwordx4 v0, s[58:59]
	s_add_i32 m0, s60, 0x2000
	s_nop 0
	global_load_lds_dwordx4 v138, s[58:59]
	s_waitcnt vmcnt(6)
	s_barrier
	s_setprio 1
	v_mfma_f32_16x16x32_bf16 v[50:53], v[212:215], v[180:183], v[50:53]
	v_mfma_f32_16x16x32_bf16 v[42:45], v[220:223], v[180:183], v[42:45]
	v_mfma_f32_16x16x32_bf16 v[34:37], v[212:215], v[188:191], v[34:37]
	v_mfma_f32_16x16x32_bf16 v[26:29], v[220:223], v[188:191], v[26:29]
	v_mfma_f32_16x16x32_bf16 v[18:21], v[212:215], v[196:199], v[18:21]
	v_mfma_f32_16x16x32_bf16 v[10:13], v[220:223], v[196:199], v[10:13]
	v_mfma_f32_16x16x32_bf16 v[6:9], v[212:215], v[204:207], v[6:9]
	v_mfma_f32_16x16x32_bf16 v[2:5], v[220:223], v[204:207], v[2:5]
	v_mfma_f32_16x16x32_bf16 v[50:53], v[216:219], v[184:187], v[50:53]
	v_mfma_f32_16x16x32_bf16 v[42:45], v[224:227], v[184:187], v[42:45]
	v_mfma_f32_16x16x32_bf16 v[34:37], v[216:219], v[192:195], v[34:37]
	v_mfma_f32_16x16x32_bf16 v[26:29], v[224:227], v[192:195], v[26:29]
	v_mfma_f32_16x16x32_bf16 v[18:21], v[216:219], v[200:203], v[18:21]
	v_mfma_f32_16x16x32_bf16 v[10:13], v[224:227], v[200:203], v[10:13]
	v_mfma_f32_16x16x32_bf16 v[6:9], v[216:219], v[208:211], v[6:9]
	v_mfma_f32_16x16x32_bf16 v[2:5], v[224:227], v[208:211], v[2:5]
	s_setprio 0
	s_add_i32 s58, 0, 0x18000
	v_add_u32_e32 v164, s58, v153
	s_barrier
	ds_read_b128 v[148:151], v164
	ds_read_b128 v[156:159], v164 offset:1024
	ds_read_b128 v[160:163], v164 offset:2048
	ds_read_b128 v[164:167], v164 offset:3072
	s_add_u32 s44, s44, 0x80000
	s_addc_u32 s45, s45, 0
	s_mov_b32 m0, s46
	ds_read_b128 v[180:183], v155 offset:32768
	ds_read_b128 v[184:187], v155 offset:33792
	ds_read_b128 v[188:191], v155 offset:34816
	ds_read_b128 v[192:195], v155 offset:35840
	ds_read_b128 v[196:199], v155 offset:36864
	ds_read_b128 v[200:203], v155 offset:37888
	ds_read_b128 v[204:207], v155 offset:38912
	ds_read_b128 v[208:211], v155 offset:39936
	global_load_lds_dwordx4 v142, s[44:45]
	s_mov_b32 m0, s47
	s_nop 0
	global_load_lds_dwordx4 v140, s[44:45]
	s_waitcnt lgkmcnt(8)
	s_barrier
	s_waitcnt lgkmcnt(0)
	s_setprio 1
	s_waitcnt lgkmcnt(0)
	v_mfma_f32_16x16x32_bf16 v[126:129], v[148:151], v[180:183], v[126:129]
	v_mfma_f32_16x16x32_bf16 v[122:125], v[160:163], v[180:183], v[122:125]
	v_mfma_f32_16x16x32_bf16 v[118:121], v[148:151], v[188:191], v[118:121]
	v_mfma_f32_16x16x32_bf16 v[110:113], v[160:163], v[188:191], v[110:113]
	v_mfma_f32_16x16x32_bf16 v[102:105], v[148:151], v[196:199], v[102:105]
	v_mfma_f32_16x16x32_bf16 v[94:97], v[160:163], v[196:199], v[94:97]
	v_mfma_f32_16x16x32_bf16 v[86:89], v[148:151], v[204:207], v[86:89]
	v_mfma_f32_16x16x32_bf16 v[78:81], v[160:163], v[204:207], v[78:81]
	v_mfma_f32_16x16x32_bf16 v[126:129], v[156:159], v[184:187], v[126:129]
	v_mfma_f32_16x16x32_bf16 v[122:125], v[164:167], v[184:187], v[122:125]
	v_mfma_f32_16x16x32_bf16 v[118:121], v[156:159], v[192:195], v[118:121]
	v_mfma_f32_16x16x32_bf16 v[110:113], v[164:167], v[192:195], v[110:113]
	v_mfma_f32_16x16x32_bf16 v[102:105], v[156:159], v[200:203], v[102:105]
	v_mfma_f32_16x16x32_bf16 v[94:97], v[164:167], v[200:203], v[94:97]
	v_mfma_f32_16x16x32_bf16 v[86:89], v[156:159], v[208:211], v[86:89]
	v_mfma_f32_16x16x32_bf16 v[78:81], v[164:167], v[208:211], v[78:81]
	s_setprio 0
	s_barrier
	s_add_i32 s44, 0, 0x1c000
	s_add_i32 s45, s58, s6
	v_add_u32_e32 v224, s44, v153
	s_add_u32 s100, s26, s10
	s_addc_u32 s101, s27, s11
	s_mov_b32 m0, s45
	ds_read_b128 v[212:215], v224
	ds_read_b128 v[216:219], v224 offset:1024
	ds_read_b128 v[220:223], v224 offset:2048
	ds_read_b128 v[224:227], v224 offset:3072
	global_load_lds_dwordx4 v0, s[100:101]
	s_add_u32 s100, s26, s10
	s_addc_u32 s101, s27, s11
	s_add_i32 m0, s45, 0x2000
	s_nop 0
	global_load_lds_dwordx4 v138, s[100:101]
	s_barrier
	s_waitcnt lgkmcnt(0)
	s_setprio 1
	s_waitcnt lgkmcnt(0)
	v_mfma_f32_16x16x32_bf16 v[114:117], v[212:215], v[180:183], v[114:117]
	v_mfma_f32_16x16x32_bf16 v[106:109], v[220:223], v[180:183], v[106:109]
	v_mfma_f32_16x16x32_bf16 v[98:101], v[212:215], v[188:191], v[98:101]
	v_mfma_f32_16x16x32_bf16 v[90:93], v[220:223], v[188:191], v[90:93]
	v_mfma_f32_16x16x32_bf16 v[82:85], v[212:215], v[196:199], v[82:85]
	v_mfma_f32_16x16x32_bf16 v[74:77], v[220:223], v[196:199], v[74:77]
	v_mfma_f32_16x16x32_bf16 v[70:73], v[212:215], v[204:207], v[70:73]
	v_mfma_f32_16x16x32_bf16 v[66:69], v[220:223], v[204:207], v[66:69]
	v_mfma_f32_16x16x32_bf16 v[114:117], v[216:219], v[184:187], v[114:117]
	v_mfma_f32_16x16x32_bf16 v[106:109], v[224:227], v[184:187], v[106:109]
	v_mfma_f32_16x16x32_bf16 v[98:101], v[216:219], v[192:195], v[98:101]
	v_mfma_f32_16x16x32_bf16 v[90:93], v[224:227], v[192:195], v[90:93]
	v_mfma_f32_16x16x32_bf16 v[82:85], v[216:219], v[200:203], v[82:85]
	v_mfma_f32_16x16x32_bf16 v[74:77], v[224:227], v[200:203], v[74:77]
	v_mfma_f32_16x16x32_bf16 v[70:73], v[216:219], v[208:211], v[70:73]
	v_mfma_f32_16x16x32_bf16 v[66:69], v[224:227], v[208:211], v[66:69]
	s_setprio 0
	s_mov_b32 m0, s48
	v_lshl_add_u64 v[134:135], v[230:231], 0, s[10:11]
	s_barrier
	ds_read_b128 v[180:183], v155 offset:49152
	ds_read_b128 v[184:187], v155 offset:50176
	ds_read_b128 v[188:191], v155 offset:51200
	ds_read_b128 v[192:195], v155 offset:52224
	ds_read_b128 v[196:199], v155 offset:53248
	ds_read_b128 v[200:203], v155 offset:54272
	ds_read_b128 v[204:207], v155 offset:55296
	ds_read_b128 v[208:211], v155 offset:56320
	global_load_lds_dwordx4 v[134:135], off
	v_lshl_add_u64 v[134:135], v[232:233], 0, s[10:11]
	s_mov_b32 m0, s49
	s_nop 0
	global_load_lds_dwordx4 v[134:135], off
	s_barrier
	s_waitcnt lgkmcnt(0)
	s_setprio 1
	s_waitcnt lgkmcnt(0)
	v_mfma_f32_16x16x32_bf16 v[62:65], v[148:151], v[180:183], v[62:65]
	v_mfma_f32_16x16x32_bf16 v[58:61], v[160:163], v[180:183], v[58:61]
	v_mfma_f32_16x16x32_bf16 v[54:57], v[148:151], v[188:191], v[54:57]
	v_mfma_f32_16x16x32_bf16 v[46:49], v[160:163], v[188:191], v[46:49]
	v_mfma_f32_16x16x32_bf16 v[38:41], v[148:151], v[196:199], v[38:41]
	v_mfma_f32_16x16x32_bf16 v[30:33], v[160:163], v[196:199], v[30:33]
	v_mfma_f32_16x16x32_bf16 v[22:25], v[148:151], v[204:207], v[22:25]
	v_mfma_f32_16x16x32_bf16 v[14:17], v[160:163], v[204:207], v[14:17]
	v_mfma_f32_16x16x32_bf16 v[62:65], v[156:159], v[184:187], v[62:65]
	v_mfma_f32_16x16x32_bf16 v[58:61], v[164:167], v[184:187], v[58:61]
	v_mfma_f32_16x16x32_bf16 v[54:57], v[156:159], v[192:195], v[54:57]
	v_mfma_f32_16x16x32_bf16 v[46:49], v[164:167], v[192:195], v[46:49]
	v_mfma_f32_16x16x32_bf16 v[38:41], v[156:159], v[200:203], v[38:41]
	v_mfma_f32_16x16x32_bf16 v[30:33], v[164:167], v[200:203], v[30:33]
	v_mfma_f32_16x16x32_bf16 v[22:25], v[156:159], v[208:211], v[22:25]
	v_mfma_f32_16x16x32_bf16 v[14:17], v[164:167], v[208:211], v[14:17]
	s_setprio 0
	s_barrier
	s_add_u32 s26, s26, 0x80080
	s_addc_u32 s27, s27, 0
	s_add_i32 s44, s44, s6
	s_mov_b32 m0, s44
	s_nop 0
	global_load_lds_dwordx4 v0, s[26:27]
	s_add_i32 m0, s44, 0x2000
	s_nop 0
	global_load_lds_dwordx4 v138, s[26:27]
	s_waitcnt vmcnt(6)
	s_barrier
	s_setprio 1
	v_mfma_f32_16x16x32_bf16 v[50:53], v[212:215], v[180:183], v[50:53]
	v_mfma_f32_16x16x32_bf16 v[42:45], v[220:223], v[180:183], v[42:45]
	v_mfma_f32_16x16x32_bf16 v[34:37], v[212:215], v[188:191], v[34:37]
	v_mfma_f32_16x16x32_bf16 v[26:29], v[220:223], v[188:191], v[26:29]
	v_mfma_f32_16x16x32_bf16 v[18:21], v[212:215], v[196:199], v[18:21]
	v_mfma_f32_16x16x32_bf16 v[10:13], v[220:223], v[196:199], v[10:13]
	v_mfma_f32_16x16x32_bf16 v[6:9], v[212:215], v[204:207], v[6:9]
	v_mfma_f32_16x16x32_bf16 v[2:5], v[220:223], v[204:207], v[2:5]
	v_mfma_f32_16x16x32_bf16 v[50:53], v[216:219], v[184:187], v[50:53]
	v_mfma_f32_16x16x32_bf16 v[42:45], v[224:227], v[184:187], v[42:45]
	v_mfma_f32_16x16x32_bf16 v[34:37], v[216:219], v[192:195], v[34:37]
	v_mfma_f32_16x16x32_bf16 v[26:29], v[224:227], v[192:195], v[26:29]
	v_mfma_f32_16x16x32_bf16 v[18:21], v[216:219], v[200:203], v[18:21]
	v_mfma_f32_16x16x32_bf16 v[10:13], v[224:227], v[200:203], v[10:13]
	v_mfma_f32_16x16x32_bf16 v[6:9], v[216:219], v[208:211], v[6:9]
	v_mfma_f32_16x16x32_bf16 v[2:5], v[224:227], v[208:211], v[2:5]
	s_setprio 0
	s_add_i32 s57, s57, 2
	s_add_u32 s42, s42, 0x100
	s_addc_u32 s43, s43, 0
	s_add_u32 s55, s55, 0x100
	s_addc_u32 s56, s56, 0
	s_cmp_gt_u32 s57, 29
	s_barrier
	s_cbranch_scc0 .LBB0_627
	v_lshl_or_b32 v134, s51, 8, v154
	v_lshl_add_u32 v158, s52, 8, v152
	v_ashrrev_i32_e32 v135, 31, v134
	v_mov_b64_e32 v[148:149], s[88:89]
	s_movk_i32 s1, 0x2200
	v_mad_i64_i32 v[156:157], s[26:27], v158, s1, v[148:149]
	v_lshlrev_b64 v[150:151], 1, v[134:135]
	v_lshl_add_u64 v[134:135], v[156:157], 0, v[150:151]
	v_cvt_pk_bf16_f32 v126, v126, v127
	v_cvt_pk_bf16_f32 v127, v128, v129
	v_cvt_pk_bf16_f32 v128, v122, v123
	v_cvt_pk_bf16_f32 v129, v124, v125
	global_store_dwordx4 v[134:135], v[126:129], off
	v_cvt_pk_bf16_f32 v114, v114, v115
	v_cvt_pk_bf16_f32 v115, v116, v117
	v_cvt_pk_bf16_f32 v116, v106, v107
	v_or_b32_e32 v106, 16, v158
	v_mad_i64_i32 v[106:107], s[26:27], v106, s1, v[148:149]
	v_cvt_pk_bf16_f32 v117, v108, v109
	global_store_dwordx4 v[134:135], v[114:117], off offset:256
	s_and_b64 vcc, exec, s[40:41]
	s_mov_b32 s51, s0
	v_lshl_add_u64 v[114:115], v[106:107], 0, v[150:151]
	v_cvt_pk_bf16_f32 v106, v118, v119
	v_cvt_pk_bf16_f32 v107, v120, v121
	v_cvt_pk_bf16_f32 v108, v110, v111
	v_cvt_pk_bf16_f32 v109, v112, v113
	global_store_dwordx4 v[114:115], v[106:109], off
	v_cvt_pk_bf16_f32 v98, v98, v99
	v_cvt_pk_bf16_f32 v99, v100, v101
	v_cvt_pk_bf16_f32 v100, v90, v91
	v_or_b32_e32 v90, 32, v158
	v_mad_i64_i32 v[90:91], s[26:27], v90, s1, v[148:149]
	v_cvt_pk_bf16_f32 v101, v92, v93
	global_store_dwordx4 v[114:115], v[98:101], off offset:256
	s_mov_b32 s52, s22
	s_mov_b64 s[42:43], s[24:25]
	v_lshl_add_u64 v[98:99], v[90:91], 0, v[150:151]
	v_cvt_pk_bf16_f32 v90, v102, v103
	v_cvt_pk_bf16_f32 v91, v104, v105
	v_cvt_pk_bf16_f32 v92, v94, v95
	v_cvt_pk_bf16_f32 v93, v96, v97
	global_store_dwordx4 v[98:99], v[90:93], off
	v_cvt_pk_bf16_f32 v82, v82, v83
	v_cvt_pk_bf16_f32 v83, v84, v85
	v_cvt_pk_bf16_f32 v84, v74, v75
	v_or_b32_e32 v74, 48, v158
	v_mad_i64_i32 v[74:75], s[26:27], v74, s1, v[148:149]
	v_cvt_pk_bf16_f32 v85, v76, v77
	global_store_dwordx4 v[98:99], v[82:85], off offset:256
	s_nop 1
	v_lshl_add_u64 v[82:83], v[74:75], 0, v[150:151]
	v_cvt_pk_bf16_f32 v74, v86, v87
	v_cvt_pk_bf16_f32 v75, v88, v89
	v_cvt_pk_bf16_f32 v76, v78, v79
	v_cvt_pk_bf16_f32 v77, v80, v81
	global_store_dwordx4 v[82:83], v[74:77], off
	v_cvt_pk_bf16_f32 v70, v70, v71
	v_cvt_pk_bf16_f32 v71, v72, v73
	v_cvt_pk_bf16_f32 v72, v66, v67
	v_add_u32_e32 v66, 0x80, v158
	v_mad_i64_i32 v[66:67], s[26:27], v66, s1, v[148:149]
	v_lshl_add_u64 v[66:67], v[66:67], 0, v[150:151]
	v_cvt_pk_bf16_f32 v73, v68, v69
	global_store_dwordx4 v[82:83], v[70:73], off offset:256
	v_cvt_pk_bf16_f32 v62, v62, v63
	v_cvt_pk_bf16_f32 v63, v64, v65
	v_cvt_pk_bf16_f32 v64, v58, v59
	v_cvt_pk_bf16_f32 v65, v60, v61
	global_store_dwordx4 v[66:67], v[62:65], off
	v_cvt_pk_bf16_f32 v50, v50, v51
	v_cvt_pk_bf16_f32 v51, v52, v53
	v_cvt_pk_bf16_f32 v52, v42, v43
	v_add_u32_e32 v42, 0x90, v158
	v_mad_i64_i32 v[42:43], s[26:27], v42, s1, v[148:149]
	v_cvt_pk_bf16_f32 v53, v44, v45
	global_store_dwordx4 v[66:67], v[50:53], off offset:256
	s_nop 1
	v_lshl_add_u64 v[50:51], v[42:43], 0, v[150:151]
	v_cvt_pk_bf16_f32 v42, v54, v55
	v_cvt_pk_bf16_f32 v43, v56, v57
	v_cvt_pk_bf16_f32 v44, v46, v47
	v_cvt_pk_bf16_f32 v45, v48, v49
	global_store_dwordx4 v[50:51], v[42:45], off
	v_cvt_pk_bf16_f32 v34, v34, v35
	v_cvt_pk_bf16_f32 v35, v36, v37
	v_cvt_pk_bf16_f32 v36, v26, v27
	v_add_u32_e32 v26, 0xa0, v158
	v_mad_i64_i32 v[26:27], s[26:27], v26, s1, v[148:149]
	v_cvt_pk_bf16_f32 v37, v28, v29
	global_store_dwordx4 v[50:51], v[34:37], off offset:256
	s_nop 1
	v_lshl_add_u64 v[34:35], v[26:27], 0, v[150:151]
	v_cvt_pk_bf16_f32 v26, v38, v39
	v_cvt_pk_bf16_f32 v27, v40, v41
	v_cvt_pk_bf16_f32 v28, v30, v31
	v_cvt_pk_bf16_f32 v29, v32, v33
	global_store_dwordx4 v[34:35], v[26:29], off
	v_cvt_pk_bf16_f32 v18, v18, v19
	v_cvt_pk_bf16_f32 v19, v20, v21
	v_cvt_pk_bf16_f32 v20, v10, v11
	v_add_u32_e32 v10, 0xb0, v158
	v_mad_i64_i32 v[10:11], s[26:27], v10, s1, v[148:149]
	v_cvt_pk_bf16_f32 v21, v12, v13
	global_store_dwordx4 v[34:35], v[18:21], off offset:256
	s_mov_b64 s[26:27], s[38:39]
	s_nop 0
	v_lshl_add_u64 v[18:19], v[10:11], 0, v[150:151]
	v_cvt_pk_bf16_f32 v10, v22, v23
	v_cvt_pk_bf16_f32 v11, v24, v25
	v_cvt_pk_bf16_f32 v12, v14, v15
	v_cvt_pk_bf16_f32 v13, v16, v17
	global_store_dwordx4 v[18:19], v[10:13], off
	v_cvt_pk_bf16_f32 v6, v6, v7
	v_cvt_pk_bf16_f32 v7, v8, v9
	v_cvt_pk_bf16_f32 v8, v2, v3
	v_cvt_pk_bf16_f32 v9, v4, v5
	global_store_dwordx4 v[18:19], v[6:9], off offset:256
	s_cbranch_vccz .LBB0_624
	s_waitcnt vmcnt(0)
	v_readlane_b32 s52, v254, 26
	v_readlane_b32 s50, v254, 28
	s_cmpk_gt_u32 s4, 0xff
	v_readlane_b32 s53, v254, 27
	v_readlane_b32 s51, v254, 29
	s_cbranch_scc1 .LBB0_631
	s_barrier

.LBB0_1034:
	s_add_u32 s26, s42, 0xfff80080
	s_addc_u32 s27, s43, -1
	s_add_i32 s58, 0, 0x10000
	v_add_u32_e32 v134, s58, v155
	ds_read_b128 v[148:151], v134
	ds_read_b128 v[158:161], v134 offset:1024
	ds_read_b128 v[162:165], v134 offset:2048
	ds_read_b128 v[180:183], v134 offset:3072
	s_cmp_eq_u32 s57, 28
	s_cselect_b32 s45, s23, s27
	s_cselect_b32 s44, s53, s26
	s_cselect_b32 s27, s1, s56
	s_cselect_b32 s26, s54, s55
	s_add_i32 m0, s7, 0xc000
	ds_read_b128 v[184:187], v157
	ds_read_b128 v[188:191], v157 offset:1024
	ds_read_b128 v[192:195], v157 offset:2048
	ds_read_b128 v[196:199], v157 offset:3072
	ds_read_b128 v[200:203], v157 offset:4096
	ds_read_b128 v[204:207], v157 offset:5120
	ds_read_b128 v[208:211], v157 offset:6144
	ds_read_b128 v[212:215], v157 offset:7168
	global_load_lds_dwordx4 v144, s[42:43]
	s_add_i32 m0, s7, 0xe000
	s_nop 0
	global_load_lds_dwordx4 v146, s[42:43]
	s_waitcnt lgkmcnt(8)
	s_barrier
	s_waitcnt lgkmcnt(0)
	s_setprio 1
	s_waitcnt lgkmcnt(0)
	v_mfma_f32_16x16x32_bf16 v[126:129], v[148:151], v[184:187], v[126:129]
	v_mfma_f32_16x16x32_bf16 v[122:125], v[162:165], v[184:187], v[122:125]
	v_mfma_f32_16x16x32_bf16 v[110:113], v[148:151], v[192:195], v[110:113]
	v_mfma_f32_16x16x32_bf16 v[106:109], v[162:165], v[192:195], v[106:109]
	v_mfma_f32_16x16x32_bf16 v[94:97], v[148:151], v[200:203], v[94:97]
	v_mfma_f32_16x16x32_bf16 v[90:93], v[162:165], v[200:203], v[90:93]
	v_mfma_f32_16x16x32_bf16 v[78:81], v[148:151], v[208:211], v[78:81]
	v_mfma_f32_16x16x32_bf16 v[74:77], v[162:165], v[208:211], v[74:77]
	v_mfma_f32_16x16x32_bf16 v[126:129], v[158:161], v[188:191], v[126:129]
	v_mfma_f32_16x16x32_bf16 v[122:125], v[180:183], v[188:191], v[122:125]
	v_mfma_f32_16x16x32_bf16 v[110:113], v[158:161], v[196:199], v[110:113]
	v_mfma_f32_16x16x32_bf16 v[106:109], v[180:183], v[196:199], v[106:109]
	v_mfma_f32_16x16x32_bf16 v[94:97], v[158:161], v[204:207], v[94:97]
	v_mfma_f32_16x16x32_bf16 v[90:93], v[180:183], v[204:207], v[90:93]
	v_mfma_f32_16x16x32_bf16 v[78:81], v[158:161], v[212:215], v[78:81]
	v_mfma_f32_16x16x32_bf16 v[74:77], v[180:183], v[212:215], v[74:77]
	s_setprio 0
	s_barrier
	s_add_i32 s60, 0, 0x14000
	v_add_u32_e32 v134, s60, v155
	s_add_i32 s58, s58, s6
	ds_read_b128 v[216:219], v134
	ds_read_b128 v[220:223], v134 offset:1024
	ds_read_b128 v[224:227], v134 offset:2048
	ds_read_b128 v[228:231], v134 offset:3072
	s_mov_b32 m0, s58
	v_lshl_add_u64 v[152:153], s[26:27], 0, v[138:139]
	global_load_lds_dwordx4 v0, s[26:27]
	s_add_i32 m0, s58, 0x2000
	s_nop 0
	global_load_lds_dwordx4 v[152:153], off
	s_barrier
	s_waitcnt lgkmcnt(0)
	s_setprio 1
	s_waitcnt lgkmcnt(0)
	v_mfma_f32_16x16x32_bf16 v[118:121], v[216:219], v[184:187], v[118:121]
	v_mfma_f32_16x16x32_bf16 v[114:117], v[224:227], v[184:187], v[114:117]
	v_mfma_f32_16x16x32_bf16 v[102:105], v[216:219], v[192:195], v[102:105]
	v_mfma_f32_16x16x32_bf16 v[98:101], v[224:227], v[192:195], v[98:101]
	v_mfma_f32_16x16x32_bf16 v[86:89], v[216:219], v[200:203], v[86:89]
	v_mfma_f32_16x16x32_bf16 v[82:85], v[224:227], v[200:203], v[82:85]
	v_mfma_f32_16x16x32_bf16 v[70:73], v[216:219], v[208:211], v[70:73]
	v_mfma_f32_16x16x32_bf16 v[66:69], v[224:227], v[208:211], v[66:69]
	v_mfma_f32_16x16x32_bf16 v[118:121], v[220:223], v[188:191], v[118:121]
	v_mfma_f32_16x16x32_bf16 v[114:117], v[228:231], v[188:191], v[114:117]
	v_mfma_f32_16x16x32_bf16 v[102:105], v[220:223], v[196:199], v[102:105]
	v_mfma_f32_16x16x32_bf16 v[98:101], v[228:231], v[196:199], v[98:101]
	v_mfma_f32_16x16x32_bf16 v[86:89], v[220:223], v[204:207], v[86:89]
	v_mfma_f32_16x16x32_bf16 v[82:85], v[228:231], v[204:207], v[82:85]
	v_mfma_f32_16x16x32_bf16 v[70:73], v[220:223], v[212:215], v[70:73]
	v_mfma_f32_16x16x32_bf16 v[66:69], v[228:231], v[212:215], v[66:69]
	s_setprio 0
	s_mov_b32 m0, s7
	v_lshl_add_u64 v[166:167], s[44:45], 0, v[142:143]
	s_barrier
	ds_read_b128 v[184:187], v157 offset:16384
	ds_read_b128 v[188:191], v157 offset:17408
	ds_read_b128 v[192:195], v157 offset:18432
	ds_read_b128 v[196:199], v157 offset:19456
	ds_read_b128 v[200:203], v157 offset:20480
	ds_read_b128 v[204:207], v157 offset:21504
	ds_read_b128 v[208:211], v157 offset:22528
	ds_read_b128 v[212:215], v157 offset:23552
	global_load_lds_dwordx4 v[166:167], off
	v_lshl_add_u64 v[232:233], s[44:45], 0, v[140:141]
	s_mov_b32 m0, s14
	s_nop 0
	global_load_lds_dwordx4 v[232:233], off
	s_barrier
	s_waitcnt lgkmcnt(0)
	s_setprio 1
	s_waitcnt lgkmcnt(0)
	v_mfma_f32_16x16x32_bf16 v[62:65], v[148:151], v[184:187], v[62:65]
	v_mfma_f32_16x16x32_bf16 v[58:61], v[162:165], v[184:187], v[58:61]
	v_mfma_f32_16x16x32_bf16 v[46:49], v[148:151], v[192:195], v[46:49]
	v_mfma_f32_16x16x32_bf16 v[42:45], v[162:165], v[192:195], v[42:45]
	v_mfma_f32_16x16x32_bf16 v[30:33], v[148:151], v[200:203], v[30:33]
	v_mfma_f32_16x16x32_bf16 v[26:29], v[162:165], v[200:203], v[26:29]
	v_mfma_f32_16x16x32_bf16 v[14:17], v[148:151], v[208:211], v[14:17]
	v_mfma_f32_16x16x32_bf16 v[10:13], v[162:165], v[208:211], v[10:13]
	v_mfma_f32_16x16x32_bf16 v[62:65], v[158:161], v[188:191], v[62:65]
	v_mfma_f32_16x16x32_bf16 v[58:61], v[180:183], v[188:191], v[58:61]
	v_mfma_f32_16x16x32_bf16 v[46:49], v[158:161], v[196:199], v[46:49]
	v_mfma_f32_16x16x32_bf16 v[42:45], v[180:183], v[196:199], v[42:45]
	v_mfma_f32_16x16x32_bf16 v[30:33], v[158:161], v[204:207], v[30:33]
	v_mfma_f32_16x16x32_bf16 v[26:29], v[180:183], v[204:207], v[26:29]
	v_mfma_f32_16x16x32_bf16 v[14:17], v[158:161], v[212:215], v[14:17]
	v_mfma_f32_16x16x32_bf16 v[10:13], v[180:183], v[212:215], v[10:13]
	s_setprio 0
	s_barrier
	s_add_u32 s58, s26, 0x80000
	s_addc_u32 s59, s27, 0
	s_add_i32 s60, s60, s6
	s_mov_b32 m0, s60
	s_nop 0
	global_load_lds_dwordx4 v0, s[58:59]
	s_add_i32 m0, s60, 0x2000
	s_nop 0
	global_load_lds_dwordx4 v138, s[58:59]
	s_waitcnt vmcnt(6)
	s_barrier
	s_setprio 1
	v_mfma_f32_16x16x32_bf16 v[54:57], v[216:219], v[184:187], v[54:57]
	v_mfma_f32_16x16x32_bf16 v[50:53], v[224:227], v[184:187], v[50:53]
	v_mfma_f32_16x16x32_bf16 v[38:41], v[216:219], v[192:195], v[38:41]
	v_mfma_f32_16x16x32_bf16 v[34:37], v[224:227], v[192:195], v[34:37]
	v_mfma_f32_16x16x32_bf16 v[22:25], v[216:219], v[200:203], v[22:25]
	v_mfma_f32_16x16x32_bf16 v[18:21], v[224:227], v[200:203], v[18:21]
	v_mfma_f32_16x16x32_bf16 v[6:9], v[216:219], v[208:211], v[6:9]
	v_mfma_f32_16x16x32_bf16 v[2:5], v[224:227], v[208:211], v[2:5]
	v_mfma_f32_16x16x32_bf16 v[54:57], v[220:223], v[188:191], v[54:57]
	v_mfma_f32_16x16x32_bf16 v[50:53], v[228:231], v[188:191], v[50:53]
	v_mfma_f32_16x16x32_bf16 v[38:41], v[220:223], v[196:199], v[38:41]
	v_mfma_f32_16x16x32_bf16 v[34:37], v[228:231], v[196:199], v[34:37]
	v_mfma_f32_16x16x32_bf16 v[22:25], v[220:223], v[204:207], v[22:25]
	v_mfma_f32_16x16x32_bf16 v[18:21], v[228:231], v[204:207], v[18:21]
	v_mfma_f32_16x16x32_bf16 v[6:9], v[220:223], v[212:215], v[6:9]
	v_mfma_f32_16x16x32_bf16 v[2:5], v[228:231], v[212:215], v[2:5]
	s_setprio 0
	s_add_i32 s58, 0, 0x18000
	v_add_u32_e32 v180, s58, v155
	s_barrier
	ds_read_b128 v[148:151], v180
	ds_read_b128 v[158:161], v180 offset:1024
	ds_read_b128 v[162:165], v180 offset:2048
	ds_read_b128 v[180:183], v180 offset:3072
	s_add_u32 s44, s44, 0x80000
	s_addc_u32 s45, s45, 0
	s_mov_b32 m0, s46
	ds_read_b128 v[184:187], v157 offset:32768
	ds_read_b128 v[188:191], v157 offset:33792
	ds_read_b128 v[192:195], v157 offset:34816
	ds_read_b128 v[196:199], v157 offset:35840
	ds_read_b128 v[200:203], v157 offset:36864
	ds_read_b128 v[204:207], v157 offset:37888
	ds_read_b128 v[208:211], v157 offset:38912
	ds_read_b128 v[212:215], v157 offset:39936
	global_load_lds_dwordx4 v142, s[44:45]
	s_mov_b32 m0, s47
	s_nop 0
	global_load_lds_dwordx4 v140, s[44:45]
	s_waitcnt lgkmcnt(8)
	s_barrier
	s_waitcnt lgkmcnt(0)
	s_setprio 1
	s_waitcnt lgkmcnt(0)
	v_mfma_f32_16x16x32_bf16 v[126:129], v[148:151], v[184:187], v[126:129]
	v_mfma_f32_16x16x32_bf16 v[122:125], v[162:165], v[184:187], v[122:125]
	v_mfma_f32_16x16x32_bf16 v[110:113], v[148:151], v[192:195], v[110:113]
	v_mfma_f32_16x16x32_bf16 v[106:109], v[162:165], v[192:195], v[106:109]
	v_mfma_f32_16x16x32_bf16 v[94:97], v[148:151], v[200:203], v[94:97]
	v_mfma_f32_16x16x32_bf16 v[90:93], v[162:165], v[200:203], v[90:93]
	v_mfma_f32_16x16x32_bf16 v[78:81], v[148:151], v[208:211], v[78:81]
	v_mfma_f32_16x16x32_bf16 v[74:77], v[162:165], v[208:211], v[74:77]
	v_mfma_f32_16x16x32_bf16 v[126:129], v[158:161], v[188:191], v[126:129]
	v_mfma_f32_16x16x32_bf16 v[122:125], v[180:183], v[188:191], v[122:125]
	v_mfma_f32_16x16x32_bf16 v[110:113], v[158:161], v[196:199], v[110:113]
	v_mfma_f32_16x16x32_bf16 v[106:109], v[180:183], v[196:199], v[106:109]
	v_mfma_f32_16x16x32_bf16 v[94:97], v[158:161], v[204:207], v[94:97]
	v_mfma_f32_16x16x32_bf16 v[90:93], v[180:183], v[204:207], v[90:93]
	v_mfma_f32_16x16x32_bf16 v[78:81], v[158:161], v[212:215], v[78:81]
	v_mfma_f32_16x16x32_bf16 v[74:77], v[180:183], v[212:215], v[74:77]
	s_setprio 0
	s_barrier
	s_add_i32 s44, 0, 0x1c000
	s_add_i32 s45, s58, s6
	v_add_u32_e32 v228, s44, v155
	s_add_u32 s100, s26, s10
	s_addc_u32 s101, s27, s11
	s_mov_b32 m0, s45
	ds_read_b128 v[216:219], v228
	ds_read_b128 v[220:223], v228 offset:1024
	ds_read_b128 v[224:227], v228 offset:2048
	ds_read_b128 v[228:231], v228 offset:3072
	global_load_lds_dwordx4 v0, s[100:101]
	s_add_u32 s100, s26, s10
	s_addc_u32 s101, s27, s11
	s_add_i32 m0, s45, 0x2000
	s_nop 0
	global_load_lds_dwordx4 v138, s[100:101]
	s_barrier
	s_waitcnt lgkmcnt(0)
	s_setprio 1
	s_waitcnt lgkmcnt(0)
	v_mfma_f32_16x16x32_bf16 v[118:121], v[216:219], v[184:187], v[118:121]
	v_mfma_f32_16x16x32_bf16 v[114:117], v[224:227], v[184:187], v[114:117]
	v_mfma_f32_16x16x32_bf16 v[102:105], v[216:219], v[192:195], v[102:105]
	v_mfma_f32_16x16x32_bf16 v[98:101], v[224:227], v[192:195], v[98:101]
	v_mfma_f32_16x16x32_bf16 v[86:89], v[216:219], v[200:203], v[86:89]
	v_mfma_f32_16x16x32_bf16 v[82:85], v[224:227], v[200:203], v[82:85]
	v_mfma_f32_16x16x32_bf16 v[70:73], v[216:219], v[208:211], v[70:73]
	v_mfma_f32_16x16x32_bf16 v[66:69], v[224:227], v[208:211], v[66:69]
	v_mfma_f32_16x16x32_bf16 v[118:121], v[220:223], v[188:191], v[118:121]
	v_mfma_f32_16x16x32_bf16 v[114:117], v[228:231], v[188:191], v[114:117]
	v_mfma_f32_16x16x32_bf16 v[102:105], v[220:223], v[196:199], v[102:105]
	v_mfma_f32_16x16x32_bf16 v[98:101], v[228:231], v[196:199], v[98:101]
	v_mfma_f32_16x16x32_bf16 v[86:89], v[220:223], v[204:207], v[86:89]
	v_mfma_f32_16x16x32_bf16 v[82:85], v[228:231], v[204:207], v[82:85]
	v_mfma_f32_16x16x32_bf16 v[70:73], v[220:223], v[212:215], v[70:73]
	v_mfma_f32_16x16x32_bf16 v[66:69], v[228:231], v[212:215], v[66:69]
	s_setprio 0
	s_mov_b32 m0, s48
	v_lshl_add_u64 v[134:135], v[166:167], 0, s[10:11]
	s_barrier
	ds_read_b128 v[184:187], v157 offset:49152
	ds_read_b128 v[188:191], v157 offset:50176
	ds_read_b128 v[192:195], v157 offset:51200
	ds_read_b128 v[196:199], v157 offset:52224
	ds_read_b128 v[200:203], v157 offset:53248
	ds_read_b128 v[204:207], v157 offset:54272
	ds_read_b128 v[208:211], v157 offset:55296
	ds_read_b128 v[212:215], v157 offset:56320
	global_load_lds_dwordx4 v[134:135], off
	v_lshl_add_u64 v[134:135], v[232:233], 0, s[10:11]
	s_mov_b32 m0, s49
	s_nop 0
	global_load_lds_dwordx4 v[134:135], off
	s_barrier
	s_waitcnt lgkmcnt(0)
	s_setprio 1
	s_waitcnt lgkmcnt(0)
	v_mfma_f32_16x16x32_bf16 v[62:65], v[148:151], v[184:187], v[62:65]
	v_mfma_f32_16x16x32_bf16 v[58:61], v[162:165], v[184:187], v[58:61]
	v_mfma_f32_16x16x32_bf16 v[46:49], v[148:151], v[192:195], v[46:49]
	v_mfma_f32_16x16x32_bf16 v[42:45], v[162:165], v[192:195], v[42:45]
	v_mfma_f32_16x16x32_bf16 v[30:33], v[148:151], v[200:203], v[30:33]
	v_mfma_f32_16x16x32_bf16 v[26:29], v[162:165], v[200:203], v[26:29]
	v_mfma_f32_16x16x32_bf16 v[14:17], v[148:151], v[208:211], v[14:17]
	v_mfma_f32_16x16x32_bf16 v[10:13], v[162:165], v[208:211], v[10:13]
	v_mfma_f32_16x16x32_bf16 v[62:65], v[158:161], v[188:191], v[62:65]
	v_mfma_f32_16x16x32_bf16 v[58:61], v[180:183], v[188:191], v[58:61]
	v_mfma_f32_16x16x32_bf16 v[46:49], v[158:161], v[196:199], v[46:49]
	v_mfma_f32_16x16x32_bf16 v[42:45], v[180:183], v[196:199], v[42:45]
	v_mfma_f32_16x16x32_bf16 v[30:33], v[158:161], v[204:207], v[30:33]
	v_mfma_f32_16x16x32_bf16 v[26:29], v[180:183], v[204:207], v[26:29]
	v_mfma_f32_16x16x32_bf16 v[14:17], v[158:161], v[212:215], v[14:17]
	v_mfma_f32_16x16x32_bf16 v[10:13], v[180:183], v[212:215], v[10:13]
	s_setprio 0
	s_barrier
	s_add_u32 s26, s26, 0x80080
	s_addc_u32 s27, s27, 0
	s_add_i32 s44, s44, s6
	s_mov_b32 m0, s44
	s_nop 0
	global_load_lds_dwordx4 v0, s[26:27]
	s_add_i32 m0, s44, 0x2000
	s_nop 0
	global_load_lds_dwordx4 v138, s[26:27]
	s_waitcnt vmcnt(6)
	s_barrier
	s_setprio 1
	v_mfma_f32_16x16x32_bf16 v[54:57], v[216:219], v[184:187], v[54:57]
	v_mfma_f32_16x16x32_bf16 v[50:53], v[224:227], v[184:187], v[50:53]
	v_mfma_f32_16x16x32_bf16 v[38:41], v[216:219], v[192:195], v[38:41]
	v_mfma_f32_16x16x32_bf16 v[34:37], v[224:227], v[192:195], v[34:37]
	v_mfma_f32_16x16x32_bf16 v[22:25], v[216:219], v[200:203], v[22:25]
	v_mfma_f32_16x16x32_bf16 v[18:21], v[224:227], v[200:203], v[18:21]
	v_mfma_f32_16x16x32_bf16 v[6:9], v[216:219], v[208:211], v[6:9]
	v_mfma_f32_16x16x32_bf16 v[2:5], v[224:227], v[208:211], v[2:5]
	v_mfma_f32_16x16x32_bf16 v[54:57], v[220:223], v[188:191], v[54:57]
	v_mfma_f32_16x16x32_bf16 v[50:53], v[228:231], v[188:191], v[50:53]
	v_mfma_f32_16x16x32_bf16 v[38:41], v[220:223], v[196:199], v[38:41]
	v_mfma_f32_16x16x32_bf16 v[34:37], v[228:231], v[196:199], v[34:37]
	v_mfma_f32_16x16x32_bf16 v[22:25], v[220:223], v[204:207], v[22:25]
	v_mfma_f32_16x16x32_bf16 v[18:21], v[228:231], v[204:207], v[18:21]
	v_mfma_f32_16x16x32_bf16 v[6:9], v[220:223], v[212:215], v[6:9]
	v_mfma_f32_16x16x32_bf16 v[2:5], v[228:231], v[212:215], v[2:5]
	s_setprio 0
	s_add_i32 s57, s57, 2
	s_add_u32 s42, s42, 0x100
	s_addc_u32 s43, s43, 0
	s_add_u32 s55, s55, 0x100
	s_addc_u32 s56, s56, 0
	s_cmp_gt_u32 s57, 29
	s_barrier
	s_cbranch_scc0 .LBB0_1034
	v_lshl_add_u32 v150, s52, 8, v154
	v_lshl_or_b32 v134, s51, 8, v156
	v_ashrrev_i32_e32 v151, 31, v150
	v_ashrrev_i32_e32 v135, 31, v134
	v_lshlrev_b64 v[148:149], 13, v[150:151]
	v_lshl_add_u64 v[148:149], s[76:77], 0, v[148:149]
	v_lshlrev_b64 v[152:153], 2, v[134:135]
	v_lshl_add_u64 v[158:159], v[148:149], 0, v[152:153]
	v_readlane_b32 s56, v254, 30
	v_readlane_b32 s54, v254, 32
	v_readlane_b32 s60, v254, 39
	s_mov_b32 s51, s0
	s_mov_b32 s52, s22
	s_mov_b64 s[42:43], s[24:25]
	v_readlane_b32 s57, v254, 31
	v_readlane_b32 s55, v254, 33
	v_readlane_b32 s44, v254, 46
	v_readlane_b32 s61, v254, 40
	v_readlane_b32 s45, v254, 47
	v_mov_b64_e32 v[162:163], v[158:159]
	global_load_dwordx4 v[180:183], v[162:163], off
	global_load_dwordx4 v[184:187], v[162:163], off offset:16
	global_load_dwordx4 v[188:191], v[162:163], off offset:512
	global_load_dwordx4 v[192:195], v[162:163], off offset:528
	s_mov_b64 s[26:27], 0x20000
	v_lshl_add_u64 v[164:165], v[158:159], 0, s[26:27]
	global_load_dwordx4 v[196:199], v[164:165], off
	global_load_dwordx4 v[200:203], v[164:165], off offset:16
	global_load_dwordx4 v[204:207], v[164:165], off offset:512
	global_load_dwordx4 v[208:211], v[164:165], off offset:528
	s_mov_b64 s[26:27], 0x40000
	v_lshl_add_u64 v[150:151], v[158:159], 0, s[26:27]
	global_load_dwordx4 v[212:215], v[150:151], off
	global_load_dwordx4 v[216:219], v[150:151], off offset:16
	global_load_dwordx4 v[220:223], v[150:151], off offset:512
	global_load_dwordx4 v[224:227], v[150:151], off offset:528
	s_waitcnt vmcnt(8)
	v_pk_add_f32 v[126:127], v[126:127], v[180:181]
	v_pk_add_f32 v[128:129], v[128:129], v[182:183]
	v_pk_add_f32 v[122:123], v[122:123], v[184:185]
	v_pk_add_f32 v[124:125], v[124:125], v[186:187]
	v_pk_add_f32 v[118:119], v[118:119], v[188:189]
	v_pk_add_f32 v[120:121], v[120:121], v[190:191]
	v_pk_add_f32 v[114:115], v[114:115], v[192:193]
	v_pk_add_f32 v[116:117], v[116:117], v[194:195]
	global_store_dwordx4 v[162:163], v[126:129], off
	global_store_dwordx4 v[162:163], v[122:125], off offset:16
	global_store_dwordx4 v[162:163], v[118:121], off offset:512
	global_store_dwordx4 v[162:163], v[114:117], off offset:528
	s_mov_b64 s[26:27], 0x60000
	v_lshl_add_u64 v[228:229], v[158:159], 0, s[26:27]
	global_load_dwordx4 v[180:183], v[228:229], off
	global_load_dwordx4 v[184:187], v[228:229], off offset:16
	global_load_dwordx4 v[188:191], v[228:229], off offset:512
	global_load_dwordx4 v[192:195], v[228:229], off offset:528
	s_waitcnt vmcnt(12)
	v_pk_add_f32 v[110:111], v[110:111], v[196:197]
	v_pk_add_f32 v[112:113], v[112:113], v[198:199]
	v_pk_add_f32 v[106:107], v[106:107], v[200:201]
	v_pk_add_f32 v[108:109], v[108:109], v[202:203]
	v_pk_add_f32 v[102:103], v[102:103], v[204:205]
	v_pk_add_f32 v[104:105], v[104:105], v[206:207]
	v_pk_add_f32 v[98:99], v[98:99], v[208:209]
	v_pk_add_f32 v[100:101], v[100:101], v[210:211]
	global_store_dwordx4 v[164:165], v[110:113], off
	global_store_dwordx4 v[164:165], v[106:109], off offset:16
	global_store_dwordx4 v[164:165], v[102:105], off offset:512
	global_store_dwordx4 v[164:165], v[98:101], off offset:528
	s_mov_b64 s[26:27], 0x100000
	v_lshl_add_u64 v[162:163], v[158:159], 0, s[26:27]
	global_load_dwordx4 v[196:199], v[162:163], off
	global_load_dwordx4 v[200:203], v[162:163], off offset:16
	global_load_dwordx4 v[204:207], v[162:163], off offset:512
	global_load_dwordx4 v[208:211], v[162:163], off offset:528
	s_waitcnt vmcnt(16)
	v_pk_add_f32 v[94:95], v[94:95], v[212:213]
	v_pk_add_f32 v[96:97], v[96:97], v[214:215]
	v_pk_add_f32 v[90:91], v[90:91], v[216:217]
	v_pk_add_f32 v[92:93], v[92:93], v[218:219]
	v_pk_add_f32 v[86:87], v[86:87], v[220:221]
	v_pk_add_f32 v[88:89], v[88:89], v[222:223]
	v_pk_add_f32 v[82:83], v[82:83], v[224:225]
	v_pk_add_f32 v[84:85], v[84:85], v[226:227]
	global_store_dwordx4 v[150:151], v[94:97], off
	global_store_dwordx4 v[150:151], v[90:93], off offset:16
	global_store_dwordx4 v[150:151], v[86:89], off offset:512
	global_store_dwordx4 v[150:151], v[82:85], off offset:528
	s_mov_b64 s[26:27], 0x120000
	v_lshl_add_u64 v[164:165], v[158:159], 0, s[26:27]
	global_load_dwordx4 v[212:215], v[164:165], off
	global_load_dwordx4 v[216:219], v[164:165], off offset:16
	global_load_dwordx4 v[220:223], v[164:165], off offset:512
	global_load_dwordx4 v[224:227], v[164:165], off offset:528
	s_waitcnt vmcnt(16)
	v_pk_add_f32 v[78:79], v[78:79], v[180:181]
	v_pk_add_f32 v[80:81], v[80:81], v[182:183]
	v_pk_add_f32 v[74:75], v[74:75], v[184:185]
	v_pk_add_f32 v[76:77], v[76:77], v[186:187]
	v_pk_add_f32 v[70:71], v[70:71], v[188:189]
	v_pk_add_f32 v[72:73], v[72:73], v[190:191]
	v_pk_add_f32 v[66:67], v[66:67], v[192:193]
	v_pk_add_f32 v[68:69], v[68:69], v[194:195]
	global_store_dwordx4 v[228:229], v[78:81], off
	global_store_dwordx4 v[228:229], v[74:77], off offset:16
	global_store_dwordx4 v[228:229], v[70:73], off offset:512
	global_store_dwordx4 v[228:229], v[66:69], off offset:528
	s_mov_b64 s[26:27], 0x140000
	v_lshl_add_u64 v[150:151], v[158:159], 0, s[26:27]
	global_load_dwordx4 v[180:183], v[150:151], off
	global_load_dwordx4 v[184:187], v[150:151], off offset:16
	global_load_dwordx4 v[188:191], v[150:151], off offset:512
	global_load_dwordx4 v[192:195], v[150:151], off offset:528
	s_waitcnt vmcnt(16)
	v_pk_add_f32 v[62:63], v[62:63], v[196:197]
	v_pk_add_f32 v[64:65], v[64:65], v[198:199]
	v_pk_add_f32 v[58:59], v[58:59], v[200:201]
	v_pk_add_f32 v[60:61], v[60:61], v[202:203]
	v_pk_add_f32 v[54:55], v[54:55], v[204:205]
	v_pk_add_f32 v[56:57], v[56:57], v[206:207]
	v_pk_add_f32 v[50:51], v[50:51], v[208:209]
	v_pk_add_f32 v[52:53], v[52:53], v[210:211]
	global_store_dwordx4 v[162:163], v[62:65], off
	global_store_dwordx4 v[162:163], v[58:61], off offset:16
	global_store_dwordx4 v[162:163], v[54:57], off offset:512
	global_store_dwordx4 v[162:163], v[50:53], off offset:528
	s_mov_b64 s[26:27], 0x160000
	v_lshl_add_u64 v[228:229], v[158:159], 0, s[26:27]
	global_load_dwordx4 v[196:199], v[228:229], off
	global_load_dwordx4 v[200:203], v[228:229], off offset:16
	global_load_dwordx4 v[204:207], v[228:229], off offset:512
	global_load_dwordx4 v[208:211], v[228:229], off offset:528
	s_waitcnt vmcnt(16)
	v_pk_add_f32 v[46:47], v[46:47], v[212:213]
	v_pk_add_f32 v[48:49], v[48:49], v[214:215]
	v_pk_add_f32 v[42:43], v[42:43], v[216:217]
	v_pk_add_f32 v[44:45], v[44:45], v[218:219]
	v_pk_add_f32 v[38:39], v[38:39], v[220:221]
	v_pk_add_f32 v[40:41], v[40:41], v[222:223]
	v_pk_add_f32 v[34:35], v[34:35], v[224:225]
	v_pk_add_f32 v[36:37], v[36:37], v[226:227]
	global_store_dwordx4 v[164:165], v[46:49], off
	global_store_dwordx4 v[164:165], v[42:45], off offset:16
	global_store_dwordx4 v[164:165], v[38:41], off offset:512
	global_store_dwordx4 v[164:165], v[34:37], off offset:528
	s_waitcnt vmcnt(12)
	v_pk_add_f32 v[30:31], v[30:31], v[180:181]
	v_pk_add_f32 v[32:33], v[32:33], v[182:183]
	v_pk_add_f32 v[26:27], v[26:27], v[184:185]
	v_pk_add_f32 v[28:29], v[28:29], v[186:187]
	v_pk_add_f32 v[22:23], v[22:23], v[188:189]
	v_pk_add_f32 v[24:25], v[24:25], v[190:191]
	v_pk_add_f32 v[18:19], v[18:19], v[192:193]
	v_pk_add_f32 v[20:21], v[20:21], v[194:195]
	global_store_dwordx4 v[150:151], v[30:33], off
	global_store_dwordx4 v[150:151], v[26:29], off offset:16
	global_store_dwordx4 v[150:151], v[22:25], off offset:512
	global_store_dwordx4 v[150:151], v[18:21], off offset:528
	s_waitcnt vmcnt(8)
	v_pk_add_f32 v[14:15], v[14:15], v[196:197]
	v_pk_add_f32 v[16:17], v[16:17], v[198:199]
	v_pk_add_f32 v[10:11], v[10:11], v[200:201]
	v_pk_add_f32 v[12:13], v[12:13], v[202:203]
	v_pk_add_f32 v[6:7], v[6:7], v[204:205]
	v_pk_add_f32 v[8:9], v[8:9], v[206:207]
	v_pk_add_f32 v[2:3], v[2:3], v[208:209]
	v_pk_add_f32 v[4:5], v[4:5], v[210:211]
	global_store_dwordx4 v[228:229], v[14:17], off
	global_store_dwordx4 v[228:229], v[10:13], off offset:16
	global_store_dwordx4 v[228:229], v[6:9], off offset:512
	global_store_dwordx4 v[228:229], v[2:5], off offset:528
	s_mov_b32 s1, 0x160000
	s_and_b64 vcc, exec, s[38:39]
	s_mov_b64 s[26:27], s[40:41]
	s_cbranch_vccz .LBB0_1027
	s_waitcnt vmcnt(0)
	v_readlane_b32 s52, v254, 26
	v_readlane_b32 s50, v254, 28
	s_mov_b64 s[58:59], s[84:85]
	s_cmpk_gt_u32 s4, 0xff
	v_readlane_b32 s53, v254, 27
	v_readlane_b32 s51, v254, 29
	s_cbranch_scc1 .LBB0_1038
	s_barrier
